# residual-row (x) stores in the norm phases no longer write-through: each row is only read back by the workgroup that wrote it; next-h stores issued before them
# speedup vs baseline: 1.0108x; 1.0022x over previous
.Lnw_skip_n0g:
	s_or_b64 exec, exec, s[40:41]
	s_barrier
	global_load_dwordx2 v[86:87], v1, s[58:59] offset:0
	global_load_dwordx2 v[90:91], v1, s[58:59] offset:512
	global_load_dwordx2 v[94:95], v1, s[58:59] offset:1024
	global_load_dwordx2 v[98:99], v1, s[58:59] offset:1536
	global_load_dwordx2 v[88:89], v1, s[60:61] offset:0
	global_load_dwordx2 v[92:93], v1, s[60:61] offset:512
	global_load_dwordx2 v[96:97], v1, s[60:61] offset:1024
	global_load_dwordx2 v[100:101], v1, s[60:61] offset:1536
	s_add_u32 s58, s58, 0x800
	s_addc_u32 s59, s59, 0
	s_add_u32 s60, s60, 0x800
	s_addc_u32 s61, s61, 0
	global_load_dwordx2 v[118:119], v1, s[58:59] offset:0
	global_load_dwordx2 v[122:123], v1, s[58:59] offset:512
	global_load_dwordx2 v[134:135], v1, s[58:59] offset:1024
	global_load_dwordx2 v[138:139], v1, s[58:59] offset:1536
	global_load_dwordx2 v[120:121], v1, s[60:61] offset:0
	global_load_dwordx2 v[124:125], v1, s[60:61] offset:512
	global_load_dwordx2 v[136:137], v1, s[60:61] offset:1024
	global_load_dwordx2 v[140:141], v1, s[60:61] offset:1536
	s_add_u32 s58, s58, 0x800
	s_addc_u32 s59, s59, 0
	s_add_u32 s60, s60, 0x800
	s_addc_u32 s61, s61, 0
	global_load_dwordx2 v[172:173], v1, s[58:59] offset:0
	global_load_dwordx2 v[176:177], v1, s[58:59] offset:512
	global_load_dwordx2 v[204:205], v1, s[58:59] offset:1024
	global_load_dwordx2 v[214:215], v1, s[58:59] offset:1536
	global_load_dwordx2 v[174:175], v1, s[60:61] offset:0
	global_load_dwordx2 v[178:179], v1, s[60:61] offset:512
	global_load_dwordx2 v[206:207], v1, s[60:61] offset:1024
	global_load_dwordx2 v[216:217], v1, s[60:61] offset:1536
	s_add_u32 s58, s58, 0x800
	s_addc_u32 s59, s59, 0
	s_add_u32 s60, s60, 0x800
	s_addc_u32 s61, s61, 0
	global_load_dwordx2 v[234:235], v1, s[58:59] offset:0
	global_load_dwordx2 v[238:239], v1, s[58:59] offset:512
	global_load_dwordx2 v[242:243], v1, s[58:59] offset:1024
	global_load_dwordx2 v[246:247], v1, s[58:59] offset:1536
	global_load_dwordx2 v[236:237], v1, s[60:61] offset:0
	global_load_dwordx2 v[240:241], v1, s[60:61] offset:512
	global_load_dwordx2 v[244:245], v1, s[60:61] offset:1024
	global_load_dwordx2 v[248:249], v1, s[60:61] offset:1536
	s_add_u32 s58, s58, 0x800
	s_addc_u32 s59, s59, 0
	s_add_u32 s60, s60, 0x800
	s_addc_u32 s61, s61, 0
	s_waitcnt vmcnt(24)
	v_lshlrev_b32_e32 v14, 16, v86
	v_and_b32_e32 v15, 0xffff0000, v86
	v_lshlrev_b32_e32 v16, 16, v88
	v_and_b32_e32 v17, 0xffff0000, v88
	v_lshlrev_b32_e32 v18, 16, v87
	v_and_b32_e32 v19, 0xffff0000, v87
	v_lshlrev_b32_e32 v20, 16, v89
	v_and_b32_e32 v21, 0xffff0000, v89
	v_pk_add_f32 v[86:87], v[14:15], v[16:17]
	v_pk_add_f32 v[88:89], v[18:19], v[20:21]
	v_lshlrev_b32_e32 v14, 16, v90
	v_and_b32_e32 v15, 0xffff0000, v90
	v_lshlrev_b32_e32 v16, 16, v92
	v_and_b32_e32 v17, 0xffff0000, v92
	v_lshlrev_b32_e32 v18, 16, v91
	v_and_b32_e32 v19, 0xffff0000, v91
	v_lshlrev_b32_e32 v20, 16, v93
	v_and_b32_e32 v21, 0xffff0000, v93
	v_pk_add_f32 v[90:91], v[14:15], v[16:17]
	v_pk_add_f32 v[92:93], v[18:19], v[20:21]
	v_lshlrev_b32_e32 v14, 16, v94
	v_and_b32_e32 v15, 0xffff0000, v94
	v_lshlrev_b32_e32 v16, 16, v96
	v_and_b32_e32 v17, 0xffff0000, v96
	v_lshlrev_b32_e32 v18, 16, v95
	v_and_b32_e32 v19, 0xffff0000, v95
	v_lshlrev_b32_e32 v20, 16, v97
	v_and_b32_e32 v21, 0xffff0000, v97
	v_pk_add_f32 v[94:95], v[14:15], v[16:17]
	v_pk_add_f32 v[96:97], v[18:19], v[20:21]
	v_lshlrev_b32_e32 v14, 16, v98
	v_and_b32_e32 v15, 0xffff0000, v98
	v_lshlrev_b32_e32 v16, 16, v100
	v_and_b32_e32 v17, 0xffff0000, v100
	v_lshlrev_b32_e32 v18, 16, v99
	v_and_b32_e32 v19, 0xffff0000, v99
	v_lshlrev_b32_e32 v20, 16, v101
	v_and_b32_e32 v21, 0xffff0000, v101
	v_pk_add_f32 v[98:99], v[14:15], v[16:17]
	v_pk_add_f32 v[100:101], v[18:19], v[20:21]
	v_pk_mul_f32 v[12:13], v[86:87], v[86:87]
	v_pk_fma_f32 v[12:13], v[88:89], v[88:89], v[12:13]
	v_pk_fma_f32 v[12:13], v[90:91], v[90:91], v[12:13]
	v_pk_fma_f32 v[12:13], v[92:93], v[92:93], v[12:13]
	v_pk_fma_f32 v[12:13], v[94:95], v[94:95], v[12:13]
	v_pk_fma_f32 v[12:13], v[96:97], v[96:97], v[12:13]
	v_pk_fma_f32 v[12:13], v[98:99], v[98:99], v[12:13]
	v_pk_fma_f32 v[12:13], v[100:101], v[100:101], v[12:13]
	v_add_f32_e32 v5, v12, v13
	s_nop 1
	v_add_f32_dpp v5, v5, v5 quad_perm:[1,0,3,2] row_mask:0xf bank_mask:0xf
	s_nop 1
	v_add_f32_dpp v5, v5, v5 quad_perm:[2,3,0,1] row_mask:0xf bank_mask:0xf
	s_nop 1
	v_add_f32_dpp v5, v5, v5 row_half_mirror row_mask:0xf bank_mask:0xf
	s_nop 1
	v_add_f32_dpp v5, v5, v5 row_mirror row_mask:0xf bank_mask:0xf
	s_nop 1
	v_add_f32_dpp v5, v5, v5 row_bcast:15 row_mask:0xa bank_mask:0xf
	s_nop 1
	v_add_f32_dpp v5, v5, v5 row_bcast:31 row_mask:0xc bank_mask:0xf
	s_nop 1
	v_readlane_b32 s32, v5, 63
	s_nop 1
	v_mov_b32_e32 v6, s32
	v_fmamk_f32 v6, v6, 0x3a800000, v146
	v_rsq_f32_e32 v6, v6
	s_nop 0
	v_mul_f32_e32 v8, 0.5, v6
	v_pk_mul_f32 v[14:15], v[86:87], v[8:9] op_sel_hi:[1,0]
	v_pk_fma_f32 v[70:71], v[22:23], v[14:15], v[70:71]
	v_pk_mul_f32 v[14:15], v[88:89], v[8:9] op_sel_hi:[1,0]
	v_pk_fma_f32 v[72:73], v[24:25], v[14:15], v[72:73]
	v_pk_mul_f32 v[14:15], v[90:91], v[8:9] op_sel_hi:[1,0]
	v_pk_fma_f32 v[74:75], v[26:27], v[14:15], v[74:75]
	v_pk_mul_f32 v[14:15], v[92:93], v[8:9] op_sel_hi:[1,0]
	v_pk_fma_f32 v[76:77], v[28:29], v[14:15], v[76:77]
	v_pk_mul_f32 v[14:15], v[94:95], v[8:9] op_sel_hi:[1,0]
	v_pk_fma_f32 v[78:79], v[30:31], v[14:15], v[78:79]
	v_pk_mul_f32 v[14:15], v[96:97], v[8:9] op_sel_hi:[1,0]
	v_pk_fma_f32 v[80:81], v[32:33], v[14:15], v[80:81]
	v_pk_mul_f32 v[14:15], v[98:99], v[8:9] op_sel_hi:[1,0]
	v_pk_fma_f32 v[82:83], v[34:35], v[14:15], v[82:83]
	v_pk_mul_f32 v[14:15], v[100:101], v[8:9] op_sel_hi:[1,0]
	v_pk_fma_f32 v[84:85], v[36:37], v[14:15], v[84:85]
	v_pk_mul_f32 v[12:13], v[70:71], v[70:71]
	v_pk_fma_f32 v[12:13], v[72:73], v[72:73], v[12:13]
	v_pk_fma_f32 v[12:13], v[74:75], v[74:75], v[12:13]
	v_pk_fma_f32 v[12:13], v[76:77], v[76:77], v[12:13]
	v_pk_fma_f32 v[12:13], v[78:79], v[78:79], v[12:13]
	v_pk_fma_f32 v[12:13], v[80:81], v[80:81], v[12:13]
	v_pk_fma_f32 v[12:13], v[82:83], v[82:83], v[12:13]
	v_pk_fma_f32 v[12:13], v[84:85], v[84:85], v[12:13]
	v_add_f32_e32 v5, v12, v13
	s_nop 1
	v_add_f32_dpp v5, v5, v5 quad_perm:[1,0,3,2] row_mask:0xf bank_mask:0xf
	s_nop 1
	v_add_f32_dpp v5, v5, v5 quad_perm:[2,3,0,1] row_mask:0xf bank_mask:0xf
	s_nop 1
	v_add_f32_dpp v5, v5, v5 row_half_mirror row_mask:0xf bank_mask:0xf
	s_nop 1
	v_add_f32_dpp v5, v5, v5 row_mirror row_mask:0xf bank_mask:0xf
	s_nop 1
	v_add_f32_dpp v5, v5, v5 row_bcast:15 row_mask:0xa bank_mask:0xf
	s_nop 1
	v_add_f32_dpp v5, v5, v5 row_bcast:31 row_mask:0xc bank_mask:0xf
	s_nop 1
	v_readlane_b32 s32, v5, 63
	s_nop 1
	v_mov_b32_e32 v6, s32
	v_fmamk_f32 v6, v6, 0x3a800000, v146
	v_rsq_f32_e32 v6, v6
	s_nop 0
	v_mov_b32_e32 v10, v6
	v_pk_mul_f32 v[14:15], v[70:71], v[10:11] op_sel_hi:[1,0]
	v_pk_fma_f32 v[16:17], v[54:55], v[14:15], v[38:39]
	v_pk_mul_f32 v[14:15], v[72:73], v[10:11] op_sel_hi:[1,0]
	v_pk_fma_f32 v[18:19], v[56:57], v[14:15], v[40:41]
	v_cvt_pk_bf16_f32 v86, v16, v17
	v_cvt_pk_bf16_f32 v87, v18, v19
	v_pk_mul_f32 v[14:15], v[74:75], v[10:11] op_sel_hi:[1,0]
	v_pk_fma_f32 v[16:17], v[58:59], v[14:15], v[42:43]
	v_pk_mul_f32 v[14:15], v[76:77], v[10:11] op_sel_hi:[1,0]
	v_pk_fma_f32 v[18:19], v[60:61], v[14:15], v[44:45]
	v_cvt_pk_bf16_f32 v90, v16, v17
	v_cvt_pk_bf16_f32 v91, v18, v19
	v_pk_mul_f32 v[14:15], v[78:79], v[10:11] op_sel_hi:[1,0]
	v_pk_fma_f32 v[16:17], v[62:63], v[14:15], v[46:47]
	v_pk_mul_f32 v[14:15], v[80:81], v[10:11] op_sel_hi:[1,0]
	v_pk_fma_f32 v[18:19], v[64:65], v[14:15], v[48:49]
	v_cvt_pk_bf16_f32 v94, v16, v17
	v_cvt_pk_bf16_f32 v95, v18, v19
	v_pk_mul_f32 v[14:15], v[82:83], v[10:11] op_sel_hi:[1,0]
	v_pk_fma_f32 v[16:17], v[66:67], v[14:15], v[50:51]
	v_pk_mul_f32 v[14:15], v[84:85], v[10:11] op_sel_hi:[1,0]
	v_pk_fma_f32 v[18:19], v[68:69], v[14:15], v[52:53]
	v_cvt_pk_bf16_f32 v98, v16, v17
	v_cvt_pk_bf16_f32 v99, v18, v19
	global_store_dwordx2 v1, v[86:87], s[62:63] offset:0 sc1
	global_store_dwordx2 v1, v[90:91], s[62:63] offset:512 sc1
	global_store_dwordx2 v1, v[94:95], s[62:63] offset:1024 sc1
	global_store_dwordx2 v1, v[98:99], s[62:63] offset:1536 sc1
	global_store_dwordx4 v0, v[70:73], s[46:47] offset:0
	global_store_dwordx4 v0, v[74:77], s[46:47] offset:1024
	global_store_dwordx4 v0, v[78:81], s[46:47] offset:2048
	global_store_dwordx4 v0, v[82:85], s[46:47] offset:3072
	s_add_u32 s46, s46, 0x1000
	s_addc_u32 s47, s47, 0
	s_add_u32 s62, s62, 0x800
	s_addc_u32 s63, s63, 0
	s_waitcnt vmcnt(24)
	v_lshlrev_b32_e32 v14, 16, v118
	v_and_b32_e32 v15, 0xffff0000, v118
	v_lshlrev_b32_e32 v16, 16, v120
	v_and_b32_e32 v17, 0xffff0000, v120
	v_lshlrev_b32_e32 v18, 16, v119
	v_and_b32_e32 v19, 0xffff0000, v119
	v_lshlrev_b32_e32 v20, 16, v121
	v_and_b32_e32 v21, 0xffff0000, v121
	v_pk_add_f32 v[118:119], v[14:15], v[16:17]
	v_pk_add_f32 v[120:121], v[18:19], v[20:21]
	v_lshlrev_b32_e32 v14, 16, v122
	v_and_b32_e32 v15, 0xffff0000, v122
	v_lshlrev_b32_e32 v16, 16, v124
	v_and_b32_e32 v17, 0xffff0000, v124
	v_lshlrev_b32_e32 v18, 16, v123
	v_and_b32_e32 v19, 0xffff0000, v123
	v_lshlrev_b32_e32 v20, 16, v125
	v_and_b32_e32 v21, 0xffff0000, v125
	v_pk_add_f32 v[122:123], v[14:15], v[16:17]
	v_pk_add_f32 v[124:125], v[18:19], v[20:21]
	v_lshlrev_b32_e32 v14, 16, v134
	v_and_b32_e32 v15, 0xffff0000, v134
	v_lshlrev_b32_e32 v16, 16, v136
	v_and_b32_e32 v17, 0xffff0000, v136
	v_lshlrev_b32_e32 v18, 16, v135
	v_and_b32_e32 v19, 0xffff0000, v135
	v_lshlrev_b32_e32 v20, 16, v137
	v_and_b32_e32 v21, 0xffff0000, v137
	v_pk_add_f32 v[134:135], v[14:15], v[16:17]
	v_pk_add_f32 v[136:137], v[18:19], v[20:21]
	v_lshlrev_b32_e32 v14, 16, v138
	v_and_b32_e32 v15, 0xffff0000, v138
	v_lshlrev_b32_e32 v16, 16, v140
	v_and_b32_e32 v17, 0xffff0000, v140
	v_lshlrev_b32_e32 v18, 16, v139
	v_and_b32_e32 v19, 0xffff0000, v139
	v_lshlrev_b32_e32 v20, 16, v141
	v_and_b32_e32 v21, 0xffff0000, v141
	v_pk_add_f32 v[138:139], v[14:15], v[16:17]
	v_pk_add_f32 v[140:141], v[18:19], v[20:21]
	v_pk_mul_f32 v[12:13], v[118:119], v[118:119]
	v_pk_fma_f32 v[12:13], v[120:121], v[120:121], v[12:13]
	v_pk_fma_f32 v[12:13], v[122:123], v[122:123], v[12:13]
	v_pk_fma_f32 v[12:13], v[124:125], v[124:125], v[12:13]
	v_pk_fma_f32 v[12:13], v[134:135], v[134:135], v[12:13]
	v_pk_fma_f32 v[12:13], v[136:137], v[136:137], v[12:13]
	v_pk_fma_f32 v[12:13], v[138:139], v[138:139], v[12:13]
	v_pk_fma_f32 v[12:13], v[140:141], v[140:141], v[12:13]
	v_add_f32_e32 v5, v12, v13
	s_nop 1
	v_add_f32_dpp v5, v5, v5 quad_perm:[1,0,3,2] row_mask:0xf bank_mask:0xf
	s_nop 1
	v_add_f32_dpp v5, v5, v5 quad_perm:[2,3,0,1] row_mask:0xf bank_mask:0xf
	s_nop 1
	v_add_f32_dpp v5, v5, v5 row_half_mirror row_mask:0xf bank_mask:0xf
	s_nop 1
	v_add_f32_dpp v5, v5, v5 row_mirror row_mask:0xf bank_mask:0xf
	s_nop 1
	v_add_f32_dpp v5, v5, v5 row_bcast:15 row_mask:0xa bank_mask:0xf
	s_nop 1
	v_add_f32_dpp v5, v5, v5 row_bcast:31 row_mask:0xc bank_mask:0xf
	s_nop 1
	v_readlane_b32 s32, v5, 63
	s_nop 1
	v_mov_b32_e32 v6, s32
	v_fmamk_f32 v6, v6, 0x3a800000, v146
	v_rsq_f32_e32 v6, v6
	s_nop 0
	v_mul_f32_e32 v8, 0.5, v6
	v_pk_mul_f32 v[14:15], v[118:119], v[8:9] op_sel_hi:[1,0]
	v_pk_fma_f32 v[102:103], v[22:23], v[14:15], v[102:103]
	v_pk_mul_f32 v[14:15], v[120:121], v[8:9] op_sel_hi:[1,0]
	v_pk_fma_f32 v[104:105], v[24:25], v[14:15], v[104:105]
	v_pk_mul_f32 v[14:15], v[122:123], v[8:9] op_sel_hi:[1,0]
	v_pk_fma_f32 v[106:107], v[26:27], v[14:15], v[106:107]
	v_pk_mul_f32 v[14:15], v[124:125], v[8:9] op_sel_hi:[1,0]
	v_pk_fma_f32 v[108:109], v[28:29], v[14:15], v[108:109]
	v_pk_mul_f32 v[14:15], v[134:135], v[8:9] op_sel_hi:[1,0]
	v_pk_fma_f32 v[110:111], v[30:31], v[14:15], v[110:111]
	v_pk_mul_f32 v[14:15], v[136:137], v[8:9] op_sel_hi:[1,0]
	v_pk_fma_f32 v[112:113], v[32:33], v[14:15], v[112:113]
	v_pk_mul_f32 v[14:15], v[138:139], v[8:9] op_sel_hi:[1,0]
	v_pk_fma_f32 v[114:115], v[34:35], v[14:15], v[114:115]
	v_pk_mul_f32 v[14:15], v[140:141], v[8:9] op_sel_hi:[1,0]
	v_pk_fma_f32 v[116:117], v[36:37], v[14:15], v[116:117]
	v_pk_mul_f32 v[12:13], v[102:103], v[102:103]
	v_pk_fma_f32 v[12:13], v[104:105], v[104:105], v[12:13]
	v_pk_fma_f32 v[12:13], v[106:107], v[106:107], v[12:13]
	v_pk_fma_f32 v[12:13], v[108:109], v[108:109], v[12:13]
	v_pk_fma_f32 v[12:13], v[110:111], v[110:111], v[12:13]
	v_pk_fma_f32 v[12:13], v[112:113], v[112:113], v[12:13]
	v_pk_fma_f32 v[12:13], v[114:115], v[114:115], v[12:13]
	v_pk_fma_f32 v[12:13], v[116:117], v[116:117], v[12:13]
	v_add_f32_e32 v5, v12, v13
	s_nop 1
	v_add_f32_dpp v5, v5, v5 quad_perm:[1,0,3,2] row_mask:0xf bank_mask:0xf
	s_nop 1
	v_add_f32_dpp v5, v5, v5 quad_perm:[2,3,0,1] row_mask:0xf bank_mask:0xf
	s_nop 1
	v_add_f32_dpp v5, v5, v5 row_half_mirror row_mask:0xf bank_mask:0xf
	s_nop 1
	v_add_f32_dpp v5, v5, v5 row_mirror row_mask:0xf bank_mask:0xf
	s_nop 1
	v_add_f32_dpp v5, v5, v5 row_bcast:15 row_mask:0xa bank_mask:0xf
	s_nop 1
	v_add_f32_dpp v5, v5, v5 row_bcast:31 row_mask:0xc bank_mask:0xf
	s_nop 1
	v_readlane_b32 s32, v5, 63
	s_nop 1
	v_mov_b32_e32 v6, s32
	v_fmamk_f32 v6, v6, 0x3a800000, v146
	v_rsq_f32_e32 v6, v6
	s_nop 0
	v_mov_b32_e32 v10, v6
	v_pk_mul_f32 v[14:15], v[102:103], v[10:11] op_sel_hi:[1,0]
	v_pk_fma_f32 v[16:17], v[54:55], v[14:15], v[38:39]
	v_pk_mul_f32 v[14:15], v[104:105], v[10:11] op_sel_hi:[1,0]
	v_pk_fma_f32 v[18:19], v[56:57], v[14:15], v[40:41]
	v_cvt_pk_bf16_f32 v118, v16, v17
	v_cvt_pk_bf16_f32 v119, v18, v19
	v_pk_mul_f32 v[14:15], v[106:107], v[10:11] op_sel_hi:[1,0]
	v_pk_fma_f32 v[16:17], v[58:59], v[14:15], v[42:43]
	v_pk_mul_f32 v[14:15], v[108:109], v[10:11] op_sel_hi:[1,0]
	v_pk_fma_f32 v[18:19], v[60:61], v[14:15], v[44:45]
	v_cvt_pk_bf16_f32 v122, v16, v17
	v_cvt_pk_bf16_f32 v123, v18, v19
	v_pk_mul_f32 v[14:15], v[110:111], v[10:11] op_sel_hi:[1,0]
	v_pk_fma_f32 v[16:17], v[62:63], v[14:15], v[46:47]
	v_pk_mul_f32 v[14:15], v[112:113], v[10:11] op_sel_hi:[1,0]
	v_pk_fma_f32 v[18:19], v[64:65], v[14:15], v[48:49]
	v_cvt_pk_bf16_f32 v134, v16, v17
	v_cvt_pk_bf16_f32 v135, v18, v19
	v_pk_mul_f32 v[14:15], v[114:115], v[10:11] op_sel_hi:[1,0]
	v_pk_fma_f32 v[16:17], v[66:67], v[14:15], v[50:51]
	v_pk_mul_f32 v[14:15], v[116:117], v[10:11] op_sel_hi:[1,0]
	v_pk_fma_f32 v[18:19], v[68:69], v[14:15], v[52:53]
	v_cvt_pk_bf16_f32 v138, v16, v17
	v_cvt_pk_bf16_f32 v139, v18, v19
	global_store_dwordx2 v1, v[118:119], s[62:63] offset:0 sc1
	global_store_dwordx2 v1, v[122:123], s[62:63] offset:512 sc1
	global_store_dwordx2 v1, v[134:135], s[62:63] offset:1024 sc1
	global_store_dwordx2 v1, v[138:139], s[62:63] offset:1536 sc1
	global_store_dwordx4 v0, v[102:105], s[46:47] offset:0
	global_store_dwordx4 v0, v[106:109], s[46:47] offset:1024
	global_store_dwordx4 v0, v[110:113], s[46:47] offset:2048
	global_store_dwordx4 v0, v[114:117], s[46:47] offset:3072
	s_add_u32 s46, s46, 0x1000
	s_addc_u32 s47, s47, 0
	s_add_u32 s62, s62, 0x800
	s_addc_u32 s63, s63, 0
	s_waitcnt vmcnt(24)
	v_lshlrev_b32_e32 v14, 16, v172
	v_and_b32_e32 v15, 0xffff0000, v172
	v_lshlrev_b32_e32 v16, 16, v174
	v_and_b32_e32 v17, 0xffff0000, v174
	v_lshlrev_b32_e32 v18, 16, v173
	v_and_b32_e32 v19, 0xffff0000, v173
	v_lshlrev_b32_e32 v20, 16, v175
	v_and_b32_e32 v21, 0xffff0000, v175
	v_pk_add_f32 v[172:173], v[14:15], v[16:17]
	v_pk_add_f32 v[174:175], v[18:19], v[20:21]
	v_lshlrev_b32_e32 v14, 16, v176
	v_and_b32_e32 v15, 0xffff0000, v176
	v_lshlrev_b32_e32 v16, 16, v178
	v_and_b32_e32 v17, 0xffff0000, v178
	v_lshlrev_b32_e32 v18, 16, v177
	v_and_b32_e32 v19, 0xffff0000, v177
	v_lshlrev_b32_e32 v20, 16, v179
	v_and_b32_e32 v21, 0xffff0000, v179
	v_pk_add_f32 v[176:177], v[14:15], v[16:17]
	v_pk_add_f32 v[178:179], v[18:19], v[20:21]
	v_lshlrev_b32_e32 v14, 16, v204
	v_and_b32_e32 v15, 0xffff0000, v204
	v_lshlrev_b32_e32 v16, 16, v206
	v_and_b32_e32 v17, 0xffff0000, v206
	v_lshlrev_b32_e32 v18, 16, v205
	v_and_b32_e32 v19, 0xffff0000, v205
	v_lshlrev_b32_e32 v20, 16, v207
	v_and_b32_e32 v21, 0xffff0000, v207
	v_pk_add_f32 v[204:205], v[14:15], v[16:17]
	v_pk_add_f32 v[206:207], v[18:19], v[20:21]
	v_lshlrev_b32_e32 v14, 16, v214
	v_and_b32_e32 v15, 0xffff0000, v214
	v_lshlrev_b32_e32 v16, 16, v216
	v_and_b32_e32 v17, 0xffff0000, v216
	v_lshlrev_b32_e32 v18, 16, v215
	v_and_b32_e32 v19, 0xffff0000, v215
	v_lshlrev_b32_e32 v20, 16, v217
	v_and_b32_e32 v21, 0xffff0000, v217
	v_pk_add_f32 v[214:215], v[14:15], v[16:17]
	v_pk_add_f32 v[216:217], v[18:19], v[20:21]
	v_pk_mul_f32 v[12:13], v[172:173], v[172:173]
	v_pk_fma_f32 v[12:13], v[174:175], v[174:175], v[12:13]
	v_pk_fma_f32 v[12:13], v[176:177], v[176:177], v[12:13]
	v_pk_fma_f32 v[12:13], v[178:179], v[178:179], v[12:13]
	v_pk_fma_f32 v[12:13], v[204:205], v[204:205], v[12:13]
	v_pk_fma_f32 v[12:13], v[206:207], v[206:207], v[12:13]
	v_pk_fma_f32 v[12:13], v[214:215], v[214:215], v[12:13]
	v_pk_fma_f32 v[12:13], v[216:217], v[216:217], v[12:13]
	v_add_f32_e32 v5, v12, v13
	s_nop 1
	v_add_f32_dpp v5, v5, v5 quad_perm:[1,0,3,2] row_mask:0xf bank_mask:0xf
	s_nop 1
	v_add_f32_dpp v5, v5, v5 quad_perm:[2,3,0,1] row_mask:0xf bank_mask:0xf
	s_nop 1
	v_add_f32_dpp v5, v5, v5 row_half_mirror row_mask:0xf bank_mask:0xf
	s_nop 1
	v_add_f32_dpp v5, v5, v5 row_mirror row_mask:0xf bank_mask:0xf
	s_nop 1
	v_add_f32_dpp v5, v5, v5 row_bcast:15 row_mask:0xa bank_mask:0xf
	s_nop 1
	v_add_f32_dpp v5, v5, v5 row_bcast:31 row_mask:0xc bank_mask:0xf
	s_nop 1
	v_readlane_b32 s32, v5, 63
	s_nop 1
	v_mov_b32_e32 v6, s32
	v_fmamk_f32 v6, v6, 0x3a800000, v146
	v_rsq_f32_e32 v6, v6
	s_nop 0
	v_mul_f32_e32 v8, 0.5, v6
	v_pk_mul_f32 v[14:15], v[172:173], v[8:9] op_sel_hi:[1,0]
	v_pk_fma_f32 v[154:155], v[22:23], v[14:15], v[154:155]
	v_pk_mul_f32 v[14:15], v[174:175], v[8:9] op_sel_hi:[1,0]
	v_pk_fma_f32 v[156:157], v[24:25], v[14:15], v[156:157]
	v_pk_mul_f32 v[14:15], v[176:177], v[8:9] op_sel_hi:[1,0]
	v_pk_fma_f32 v[158:159], v[26:27], v[14:15], v[158:159]
	v_pk_mul_f32 v[14:15], v[178:179], v[8:9] op_sel_hi:[1,0]
	v_pk_fma_f32 v[160:161], v[28:29], v[14:15], v[160:161]
	v_pk_mul_f32 v[14:15], v[204:205], v[8:9] op_sel_hi:[1,0]
	v_pk_fma_f32 v[162:163], v[30:31], v[14:15], v[162:163]
	v_pk_mul_f32 v[14:15], v[206:207], v[8:9] op_sel_hi:[1,0]
	v_pk_fma_f32 v[164:165], v[32:33], v[14:15], v[164:165]
	v_pk_mul_f32 v[14:15], v[214:215], v[8:9] op_sel_hi:[1,0]
	v_pk_fma_f32 v[168:169], v[34:35], v[14:15], v[168:169]
	v_pk_mul_f32 v[14:15], v[216:217], v[8:9] op_sel_hi:[1,0]
	v_pk_fma_f32 v[170:171], v[36:37], v[14:15], v[170:171]
	v_pk_mul_f32 v[12:13], v[154:155], v[154:155]
	v_pk_fma_f32 v[12:13], v[156:157], v[156:157], v[12:13]
	v_pk_fma_f32 v[12:13], v[158:159], v[158:159], v[12:13]
	v_pk_fma_f32 v[12:13], v[160:161], v[160:161], v[12:13]
	v_pk_fma_f32 v[12:13], v[162:163], v[162:163], v[12:13]
	v_pk_fma_f32 v[12:13], v[164:165], v[164:165], v[12:13]
	v_pk_fma_f32 v[12:13], v[168:169], v[168:169], v[12:13]
	v_pk_fma_f32 v[12:13], v[170:171], v[170:171], v[12:13]
	v_add_f32_e32 v5, v12, v13
	s_nop 1
	v_add_f32_dpp v5, v5, v5 quad_perm:[1,0,3,2] row_mask:0xf bank_mask:0xf
	s_nop 1
	v_add_f32_dpp v5, v5, v5 quad_perm:[2,3,0,1] row_mask:0xf bank_mask:0xf
	s_nop 1
	v_add_f32_dpp v5, v5, v5 row_half_mirror row_mask:0xf bank_mask:0xf
	s_nop 1
	v_add_f32_dpp v5, v5, v5 row_mirror row_mask:0xf bank_mask:0xf
	s_nop 1
	v_add_f32_dpp v5, v5, v5 row_bcast:15 row_mask:0xa bank_mask:0xf
	s_nop 1
	v_add_f32_dpp v5, v5, v5 row_bcast:31 row_mask:0xc bank_mask:0xf
	s_nop 1
	v_readlane_b32 s32, v5, 63
	s_nop 1
	v_mov_b32_e32 v6, s32
	v_fmamk_f32 v6, v6, 0x3a800000, v146
	v_rsq_f32_e32 v6, v6
	s_nop 0
	v_mov_b32_e32 v10, v6
	v_pk_mul_f32 v[14:15], v[154:155], v[10:11] op_sel_hi:[1,0]
	v_pk_fma_f32 v[16:17], v[54:55], v[14:15], v[38:39]
	v_pk_mul_f32 v[14:15], v[156:157], v[10:11] op_sel_hi:[1,0]
	v_pk_fma_f32 v[18:19], v[56:57], v[14:15], v[40:41]
	v_cvt_pk_bf16_f32 v172, v16, v17
	v_cvt_pk_bf16_f32 v173, v18, v19
	v_pk_mul_f32 v[14:15], v[158:159], v[10:11] op_sel_hi:[1,0]
	v_pk_fma_f32 v[16:17], v[58:59], v[14:15], v[42:43]
	v_pk_mul_f32 v[14:15], v[160:161], v[10:11] op_sel_hi:[1,0]
	v_pk_fma_f32 v[18:19], v[60:61], v[14:15], v[44:45]
	v_cvt_pk_bf16_f32 v176, v16, v17
	v_cvt_pk_bf16_f32 v177, v18, v19
	v_pk_mul_f32 v[14:15], v[162:163], v[10:11] op_sel_hi:[1,0]
	v_pk_fma_f32 v[16:17], v[62:63], v[14:15], v[46:47]
	v_pk_mul_f32 v[14:15], v[164:165], v[10:11] op_sel_hi:[1,0]
	v_pk_fma_f32 v[18:19], v[64:65], v[14:15], v[48:49]
	v_cvt_pk_bf16_f32 v204, v16, v17
	v_cvt_pk_bf16_f32 v205, v18, v19
	v_pk_mul_f32 v[14:15], v[168:169], v[10:11] op_sel_hi:[1,0]
	v_pk_fma_f32 v[16:17], v[66:67], v[14:15], v[50:51]
	v_pk_mul_f32 v[14:15], v[170:171], v[10:11] op_sel_hi:[1,0]
	v_pk_fma_f32 v[18:19], v[68:69], v[14:15], v[52:53]
	v_cvt_pk_bf16_f32 v214, v16, v17
	v_cvt_pk_bf16_f32 v215, v18, v19
	global_store_dwordx2 v1, v[172:173], s[62:63] offset:0 sc1
	global_store_dwordx2 v1, v[176:177], s[62:63] offset:512 sc1
	global_store_dwordx2 v1, v[204:205], s[62:63] offset:1024 sc1
	global_store_dwordx2 v1, v[214:215], s[62:63] offset:1536 sc1
	global_store_dwordx4 v0, v[154:157], s[46:47] offset:0
	global_store_dwordx4 v0, v[158:161], s[46:47] offset:1024
	global_store_dwordx4 v0, v[162:165], s[46:47] offset:2048
	global_store_dwordx4 v0, v[168:171], s[46:47] offset:3072
	s_add_u32 s46, s46, 0x1000
	s_addc_u32 s47, s47, 0
	s_add_u32 s62, s62, 0x800
	s_addc_u32 s63, s63, 0
	s_waitcnt vmcnt(24)
	v_lshlrev_b32_e32 v14, 16, v234
	v_and_b32_e32 v15, 0xffff0000, v234
	v_lshlrev_b32_e32 v16, 16, v236
	v_and_b32_e32 v17, 0xffff0000, v236
	v_lshlrev_b32_e32 v18, 16, v235
	v_and_b32_e32 v19, 0xffff0000, v235
	v_lshlrev_b32_e32 v20, 16, v237
	v_and_b32_e32 v21, 0xffff0000, v237
	v_pk_add_f32 v[234:235], v[14:15], v[16:17]
	v_pk_add_f32 v[236:237], v[18:19], v[20:21]
	v_lshlrev_b32_e32 v14, 16, v238
	v_and_b32_e32 v15, 0xffff0000, v238
	v_lshlrev_b32_e32 v16, 16, v240
	v_and_b32_e32 v17, 0xffff0000, v240
	v_lshlrev_b32_e32 v18, 16, v239
	v_and_b32_e32 v19, 0xffff0000, v239
	v_lshlrev_b32_e32 v20, 16, v241
	v_and_b32_e32 v21, 0xffff0000, v241
	v_pk_add_f32 v[238:239], v[14:15], v[16:17]
	v_pk_add_f32 v[240:241], v[18:19], v[20:21]
	v_lshlrev_b32_e32 v14, 16, v242
	v_and_b32_e32 v15, 0xffff0000, v242
	v_lshlrev_b32_e32 v16, 16, v244
	v_and_b32_e32 v17, 0xffff0000, v244
	v_lshlrev_b32_e32 v18, 16, v243
	v_and_b32_e32 v19, 0xffff0000, v243
	v_lshlrev_b32_e32 v20, 16, v245
	v_and_b32_e32 v21, 0xffff0000, v245
	v_pk_add_f32 v[242:243], v[14:15], v[16:17]
	v_pk_add_f32 v[244:245], v[18:19], v[20:21]
	v_lshlrev_b32_e32 v14, 16, v246
	v_and_b32_e32 v15, 0xffff0000, v246
	v_lshlrev_b32_e32 v16, 16, v248
	v_and_b32_e32 v17, 0xffff0000, v248
	v_lshlrev_b32_e32 v18, 16, v247
	v_and_b32_e32 v19, 0xffff0000, v247
	v_lshlrev_b32_e32 v20, 16, v249
	v_and_b32_e32 v21, 0xffff0000, v249
	v_pk_add_f32 v[246:247], v[14:15], v[16:17]
	v_pk_add_f32 v[248:249], v[18:19], v[20:21]
	v_pk_mul_f32 v[12:13], v[234:235], v[234:235]
	v_pk_fma_f32 v[12:13], v[236:237], v[236:237], v[12:13]
	v_pk_fma_f32 v[12:13], v[238:239], v[238:239], v[12:13]
	v_pk_fma_f32 v[12:13], v[240:241], v[240:241], v[12:13]
	v_pk_fma_f32 v[12:13], v[242:243], v[242:243], v[12:13]
	v_pk_fma_f32 v[12:13], v[244:245], v[244:245], v[12:13]
	v_pk_fma_f32 v[12:13], v[246:247], v[246:247], v[12:13]
	v_pk_fma_f32 v[12:13], v[248:249], v[248:249], v[12:13]
	v_add_f32_e32 v5, v12, v13
	s_nop 1
	v_add_f32_dpp v5, v5, v5 quad_perm:[1,0,3,2] row_mask:0xf bank_mask:0xf
	s_nop 1
	v_add_f32_dpp v5, v5, v5 quad_perm:[2,3,0,1] row_mask:0xf bank_mask:0xf
	s_nop 1
	v_add_f32_dpp v5, v5, v5 row_half_mirror row_mask:0xf bank_mask:0xf
	s_nop 1
	v_add_f32_dpp v5, v5, v5 row_mirror row_mask:0xf bank_mask:0xf
	s_nop 1
	v_add_f32_dpp v5, v5, v5 row_bcast:15 row_mask:0xa bank_mask:0xf
	s_nop 1
	v_add_f32_dpp v5, v5, v5 row_bcast:31 row_mask:0xc bank_mask:0xf
	s_nop 1
	v_readlane_b32 s32, v5, 63
	s_nop 1
	v_mov_b32_e32 v6, s32
	v_fmamk_f32 v6, v6, 0x3a800000, v146
	v_rsq_f32_e32 v6, v6
	s_nop 0
	v_mul_f32_e32 v8, 0.5, v6
	v_pk_mul_f32 v[14:15], v[234:235], v[8:9] op_sel_hi:[1,0]
	v_pk_fma_f32 v[218:219], v[22:23], v[14:15], v[218:219]
	v_pk_mul_f32 v[14:15], v[236:237], v[8:9] op_sel_hi:[1,0]
	v_pk_fma_f32 v[220:221], v[24:25], v[14:15], v[220:221]
	v_pk_mul_f32 v[14:15], v[238:239], v[8:9] op_sel_hi:[1,0]
	v_pk_fma_f32 v[222:223], v[26:27], v[14:15], v[222:223]
	v_pk_mul_f32 v[14:15], v[240:241], v[8:9] op_sel_hi:[1,0]
	v_pk_fma_f32 v[224:225], v[28:29], v[14:15], v[224:225]
	v_pk_mul_f32 v[14:15], v[242:243], v[8:9] op_sel_hi:[1,0]
	v_pk_fma_f32 v[226:227], v[30:31], v[14:15], v[226:227]
	v_pk_mul_f32 v[14:15], v[244:245], v[8:9] op_sel_hi:[1,0]
	v_pk_fma_f32 v[228:229], v[32:33], v[14:15], v[228:229]
	v_pk_mul_f32 v[14:15], v[246:247], v[8:9] op_sel_hi:[1,0]
	v_pk_fma_f32 v[230:231], v[34:35], v[14:15], v[230:231]
	v_pk_mul_f32 v[14:15], v[248:249], v[8:9] op_sel_hi:[1,0]
	v_pk_fma_f32 v[232:233], v[36:37], v[14:15], v[232:233]
	v_pk_mul_f32 v[12:13], v[218:219], v[218:219]
	v_pk_fma_f32 v[12:13], v[220:221], v[220:221], v[12:13]
	v_pk_fma_f32 v[12:13], v[222:223], v[222:223], v[12:13]
	v_pk_fma_f32 v[12:13], v[224:225], v[224:225], v[12:13]
	v_pk_fma_f32 v[12:13], v[226:227], v[226:227], v[12:13]
	v_pk_fma_f32 v[12:13], v[228:229], v[228:229], v[12:13]
	v_pk_fma_f32 v[12:13], v[230:231], v[230:231], v[12:13]
	v_pk_fma_f32 v[12:13], v[232:233], v[232:233], v[12:13]
	v_add_f32_e32 v5, v12, v13
	s_nop 1
	v_add_f32_dpp v5, v5, v5 quad_perm:[1,0,3,2] row_mask:0xf bank_mask:0xf
	s_nop 1
	v_add_f32_dpp v5, v5, v5 quad_perm:[2,3,0,1] row_mask:0xf bank_mask:0xf
	s_nop 1
	v_add_f32_dpp v5, v5, v5 row_half_mirror row_mask:0xf bank_mask:0xf
	s_nop 1
	v_add_f32_dpp v5, v5, v5 row_mirror row_mask:0xf bank_mask:0xf
	s_nop 1
	v_add_f32_dpp v5, v5, v5 row_bcast:15 row_mask:0xa bank_mask:0xf
	s_nop 1
	v_add_f32_dpp v5, v5, v5 row_bcast:31 row_mask:0xc bank_mask:0xf
	s_nop 1
	v_readlane_b32 s32, v5, 63
	s_nop 1
	v_mov_b32_e32 v6, s32
	v_fmamk_f32 v6, v6, 0x3a800000, v146
	v_rsq_f32_e32 v6, v6
	s_nop 0
	v_mov_b32_e32 v10, v6
	v_pk_mul_f32 v[14:15], v[218:219], v[10:11] op_sel_hi:[1,0]
	v_pk_fma_f32 v[16:17], v[54:55], v[14:15], v[38:39]
	v_pk_mul_f32 v[14:15], v[220:221], v[10:11] op_sel_hi:[1,0]
	v_pk_fma_f32 v[18:19], v[56:57], v[14:15], v[40:41]
	v_cvt_pk_bf16_f32 v234, v16, v17
	v_cvt_pk_bf16_f32 v235, v18, v19
	v_pk_mul_f32 v[14:15], v[222:223], v[10:11] op_sel_hi:[1,0]
	v_pk_fma_f32 v[16:17], v[58:59], v[14:15], v[42:43]
	v_pk_mul_f32 v[14:15], v[224:225], v[10:11] op_sel_hi:[1,0]
	v_pk_fma_f32 v[18:19], v[60:61], v[14:15], v[44:45]
	v_cvt_pk_bf16_f32 v238, v16, v17
	v_cvt_pk_bf16_f32 v239, v18, v19
	v_pk_mul_f32 v[14:15], v[226:227], v[10:11] op_sel_hi:[1,0]
	v_pk_fma_f32 v[16:17], v[62:63], v[14:15], v[46:47]
	v_pk_mul_f32 v[14:15], v[228:229], v[10:11] op_sel_hi:[1,0]
	v_pk_fma_f32 v[18:19], v[64:65], v[14:15], v[48:49]
	v_cvt_pk_bf16_f32 v242, v16, v17
	v_cvt_pk_bf16_f32 v243, v18, v19
	v_pk_mul_f32 v[14:15], v[230:231], v[10:11] op_sel_hi:[1,0]
	v_pk_fma_f32 v[16:17], v[66:67], v[14:15], v[50:51]
	v_pk_mul_f32 v[14:15], v[232:233], v[10:11] op_sel_hi:[1,0]
	v_pk_fma_f32 v[18:19], v[68:69], v[14:15], v[52:53]
	v_cvt_pk_bf16_f32 v246, v16, v17
	v_cvt_pk_bf16_f32 v247, v18, v19
	global_store_dwordx2 v1, v[234:235], s[62:63] offset:0 sc1
	global_store_dwordx2 v1, v[238:239], s[62:63] offset:512 sc1
	global_store_dwordx2 v1, v[242:243], s[62:63] offset:1024 sc1
	global_store_dwordx2 v1, v[246:247], s[62:63] offset:1536 sc1
	global_store_dwordx4 v0, v[218:221], s[46:47] offset:0
	global_store_dwordx4 v0, v[222:225], s[46:47] offset:1024
	global_store_dwordx4 v0, v[226:229], s[46:47] offset:2048
	global_store_dwordx4 v0, v[230:233], s[46:47] offset:3072
	s_add_u32 s46, s46, 0x1000
	s_addc_u32 s47, s47, 0
	s_add_u32 s62, s62, 0x800
	s_addc_u32 s63, s63, 0
	s_branch .Lnorm0_done
.Lnorm0_first:
	v_readlane_b32 s2, v255, 0
	v_readfirstlane_b32 s7, v147
	s_load_dwordx2 s[4:5], s[0:1], 0x90
	s_load_dwordx2 s[12:13], s[0:1], 0x98
	s_load_dwordx2 s[14:15], s[0:1], 0x40
	s_load_dwordx2 s[58:59], s[0:1], 0x0
	s_load_dwordx2 s[60:61], s[0:1], 0x8
	v_and_b32_e32 v0, 63, v147
	v_lshlrev_b32_e32 v1, 3, v0
	v_lshlrev_b32_e32 v0, 4, v0
	s_lshr_b32 s7, s7, 6
	s_and_b32 s27, s2, 6
	s_lshl_b32 s27, s27, 5
	s_and_b32 s37, s2, 0x39
	s_or_b32 s27, s27, s37
	s_lshr_b32 s37, s2, 6
	s_lshl_b32 s37, s37, 1
	s_or_b32 s2, s27, s37
	s_lshl_b32 s2, s2, 3
	s_add_u32 s2, s2, s7
	s_lshl_b32 s24, s2, 2
	s_sub_u32 s27, s24, 0x1000
	s_lshr_b32 s27, s27, 10
	s_add_u32 s27, s27, 1
	s_cmp_lt_u32 s24, 0x1000
	s_cselect_b32 s30, 0, s27
	v_mov_b32_e32 v3, v0
	v_add_u32_e32 v4, 0x1000, v0
	s_waitcnt lgkmcnt(0)
	s_lshl_b32 s27, s24, 11
	s_add_u32 s62, s12, s27
	s_addc_u32 s63, s13, 0
	s_add_u32 s62, s62, 0x1000000
	s_addc_u32 s63, s63, 0
	s_lshl_b32 s27, s24, 12
	s_add_u32 s46, s4, s27
	s_addc_u32 s47, s5, 0
	s_sub_u32 s37, s27, 0x1000000
	s_cmp_lt_u32 s24, 0x1000
	s_cselect_b32 s4, s58, s60
	s_cselect_b32 s5, s59, s61
	s_cselect_b32 s27, s27, s37
	s_add_u32 s4, s4, s27
	s_addc_u32 s5, s5, 0
	s_mul_i32 s27, s70, 5
	s_add_u32 s27, s27, s30
	s_mul_i32 s27, s27, 0x9000
	s_add_u32 s27, s27, 0x100000
	s_add_u32 s88, s12, s27
	s_addc_u32 s89, s13, 0
	s_mul_i32 s27, s70, 0x3000
	s_add_u32 s14, s14, s27
	s_addc_u32 s15, s15, 0
	global_load_dwordx4 v[22:25], v3, s[88:89] offset:0
	global_load_dwordx4 v[38:41], v4, s[88:89] offset:0
	global_load_dwordx4 v[54:57], v0, s[14:15] offset:0
	global_load_dwordx4 v[26:29], v3, s[88:89] offset:1024
	global_load_dwordx4 v[42:45], v4, s[88:89] offset:1024
	global_load_dwordx4 v[58:61], v0, s[14:15] offset:1024
	global_load_dwordx4 v[30:33], v3, s[88:89] offset:2048
	global_load_dwordx4 v[46:49], v4, s[88:89] offset:2048
	global_load_dwordx4 v[62:65], v0, s[14:15] offset:2048
	global_load_dwordx4 v[34:37], v3, s[88:89] offset:3072
	global_load_dwordx4 v[50:53], v4, s[88:89] offset:3072
	global_load_dwordx4 v[66:69], v0, s[14:15] offset:3072
	global_load_dwordx4 v[70:73], v0, s[4:5] offset:0 nt
	global_load_dwordx4 v[74:77], v0, s[4:5] offset:1024 nt
	global_load_dwordx4 v[78:81], v0, s[4:5] offset:2048 nt
	global_load_dwordx4 v[82:85], v0, s[4:5] offset:3072 nt
	s_add_u32 s4, s4, 0x1000
	s_addc_u32 s5, s5, 0
	global_load_dwordx4 v[86:89], v0, s[4:5] offset:0 nt
	global_load_dwordx4 v[90:93], v0, s[4:5] offset:1024 nt
	global_load_dwordx4 v[94:97], v0, s[4:5] offset:2048 nt
	global_load_dwordx4 v[98:101], v0, s[4:5] offset:3072 nt
	s_add_u32 s4, s4, 0x1000
	s_addc_u32 s5, s5, 0
	global_load_dwordx4 v[102:105], v0, s[4:5] offset:0 nt
	global_load_dwordx4 v[106:109], v0, s[4:5] offset:1024 nt
	global_load_dwordx4 v[110:113], v0, s[4:5] offset:2048 nt
	global_load_dwordx4 v[114:117], v0, s[4:5] offset:3072 nt
	s_add_u32 s4, s4, 0x1000
	s_addc_u32 s5, s5, 0
	s_waitcnt vmcnt(8)
	v_pk_add_f32 v[38:39], v[38:39], 1.0 op_sel_hi:[1,0]
	v_pk_add_f32 v[40:41], v[40:41], 1.0 op_sel_hi:[1,0]
	v_pk_add_f32 v[42:43], v[42:43], 1.0 op_sel_hi:[1,0]
	v_pk_add_f32 v[44:45], v[44:45], 1.0 op_sel_hi:[1,0]
	v_pk_add_f32 v[46:47], v[46:47], 1.0 op_sel_hi:[1,0]
	v_pk_add_f32 v[48:49], v[48:49], 1.0 op_sel_hi:[1,0]
	v_pk_add_f32 v[50:51], v[50:51], 1.0 op_sel_hi:[1,0]
	v_pk_add_f32 v[52:53], v[52:53], 1.0 op_sel_hi:[1,0]
	v_pk_mul_f32 v[12:13], v[70:71], v[70:71]
	v_pk_fma_f32 v[12:13], v[72:73], v[72:73], v[12:13]
	v_pk_fma_f32 v[12:13], v[74:75], v[74:75], v[12:13]
	v_pk_fma_f32 v[12:13], v[76:77], v[76:77], v[12:13]
	v_pk_fma_f32 v[12:13], v[78:79], v[78:79], v[12:13]
	v_pk_fma_f32 v[12:13], v[80:81], v[80:81], v[12:13]
	v_pk_fma_f32 v[12:13], v[82:83], v[82:83], v[12:13]
	v_pk_fma_f32 v[12:13], v[84:85], v[84:85], v[12:13]
	v_add_f32_e32 v5, v12, v13
	s_nop 1
	v_add_f32_dpp v5, v5, v5 quad_perm:[1,0,3,2] row_mask:0xf bank_mask:0xf
	s_nop 1
	v_add_f32_dpp v5, v5, v5 quad_perm:[2,3,0,1] row_mask:0xf bank_mask:0xf
	s_nop 1
	v_add_f32_dpp v5, v5, v5 row_half_mirror row_mask:0xf bank_mask:0xf
	s_nop 1
	v_add_f32_dpp v5, v5, v5 row_mirror row_mask:0xf bank_mask:0xf
	s_nop 1
	v_add_f32_dpp v5, v5, v5 row_bcast:15 row_mask:0xa bank_mask:0xf
	s_nop 1
	v_add_f32_dpp v5, v5, v5 row_bcast:31 row_mask:0xc bank_mask:0xf
	s_nop 1
	v_readlane_b32 s32, v5, 63
	s_nop 1
	v_mov_b32_e32 v6, s32
	v_fmamk_f32 v6, v6, 0x3a800000, v146
	v_rsq_f32_e32 v6, v6
	s_nop 0
	v_mov_b32_e32 v10, v6
	v_pk_mul_f32 v[14:15], v[70:71], v[10:11] op_sel_hi:[1,0]
	v_pk_mul_f32 v[14:15], v[54:55], v[14:15]
	v_pk_fma_f32 v[16:17], v[38:39], v[14:15], v[22:23]
	v_pk_mul_f32 v[14:15], v[72:73], v[10:11] op_sel_hi:[1,0]
	v_pk_mul_f32 v[14:15], v[56:57], v[14:15]
	v_pk_fma_f32 v[18:19], v[40:41], v[14:15], v[24:25]
	v_cvt_pk_bf16_f32 v118, v16, v17
	v_cvt_pk_bf16_f32 v119, v18, v19
	v_pk_mul_f32 v[14:15], v[74:75], v[10:11] op_sel_hi:[1,0]
	v_pk_mul_f32 v[14:15], v[58:59], v[14:15]
	v_pk_fma_f32 v[16:17], v[42:43], v[14:15], v[26:27]
	v_pk_mul_f32 v[14:15], v[76:77], v[10:11] op_sel_hi:[1,0]
	v_pk_mul_f32 v[14:15], v[60:61], v[14:15]
	v_pk_fma_f32 v[18:19], v[44:45], v[14:15], v[28:29]
	v_cvt_pk_bf16_f32 v120, v16, v17
	v_cvt_pk_bf16_f32 v121, v18, v19
	v_pk_mul_f32 v[14:15], v[78:79], v[10:11] op_sel_hi:[1,0]
	v_pk_mul_f32 v[14:15], v[62:63], v[14:15]
	v_pk_fma_f32 v[16:17], v[46:47], v[14:15], v[30:31]
	v_pk_mul_f32 v[14:15], v[80:81], v[10:11] op_sel_hi:[1,0]
	v_pk_mul_f32 v[14:15], v[64:65], v[14:15]
	v_pk_fma_f32 v[18:19], v[48:49], v[14:15], v[32:33]
	v_cvt_pk_bf16_f32 v122, v16, v17
	v_cvt_pk_bf16_f32 v123, v18, v19
	v_pk_mul_f32 v[14:15], v[82:83], v[10:11] op_sel_hi:[1,0]
	v_pk_mul_f32 v[14:15], v[66:67], v[14:15]
	v_pk_fma_f32 v[16:17], v[50:51], v[14:15], v[34:35]
	v_pk_mul_f32 v[14:15], v[84:85], v[10:11] op_sel_hi:[1,0]
	v_pk_mul_f32 v[14:15], v[68:69], v[14:15]
	v_pk_fma_f32 v[18:19], v[52:53], v[14:15], v[36:37]
	v_cvt_pk_bf16_f32 v124, v16, v17
	v_cvt_pk_bf16_f32 v125, v18, v19
	global_store_dwordx2 v1, v[118:119], s[62:63] offset:0 sc1
	global_store_dwordx2 v1, v[120:121], s[62:63] offset:512 sc1
	global_store_dwordx2 v1, v[122:123], s[62:63] offset:1024 sc1
	global_store_dwordx2 v1, v[124:125], s[62:63] offset:1536 sc1
	global_store_dwordx4 v0, v[70:73], s[46:47] offset:0
	global_store_dwordx4 v0, v[74:77], s[46:47] offset:1024
	global_store_dwordx4 v0, v[78:81], s[46:47] offset:2048
	global_store_dwordx4 v0, v[82:85], s[46:47] offset:3072
	s_add_u32 s46, s46, 0x1000
	s_addc_u32 s47, s47, 0
	s_add_u32 s62, s62, 0x800
	s_addc_u32 s63, s63, 0
	s_nop 1
	global_load_dwordx4 v[70:73], v0, s[4:5] offset:0 nt
	global_load_dwordx4 v[74:77], v0, s[4:5] offset:1024 nt
	global_load_dwordx4 v[78:81], v0, s[4:5] offset:2048 nt
	global_load_dwordx4 v[82:85], v0, s[4:5] offset:3072 nt
	s_add_u32 s4, s4, 0x1000
	s_addc_u32 s5, s5, 0
	s_waitcnt vmcnt(16)
	v_pk_mul_f32 v[12:13], v[86:87], v[86:87]
	v_pk_fma_f32 v[12:13], v[88:89], v[88:89], v[12:13]
	v_pk_fma_f32 v[12:13], v[90:91], v[90:91], v[12:13]
	v_pk_fma_f32 v[12:13], v[92:93], v[92:93], v[12:13]
	v_pk_fma_f32 v[12:13], v[94:95], v[94:95], v[12:13]
	v_pk_fma_f32 v[12:13], v[96:97], v[96:97], v[12:13]
	v_pk_fma_f32 v[12:13], v[98:99], v[98:99], v[12:13]
	v_pk_fma_f32 v[12:13], v[100:101], v[100:101], v[12:13]
	v_add_f32_e32 v5, v12, v13
	s_nop 1
	v_add_f32_dpp v5, v5, v5 quad_perm:[1,0,3,2] row_mask:0xf bank_mask:0xf
	s_nop 1
	v_add_f32_dpp v5, v5, v5 quad_perm:[2,3,0,1] row_mask:0xf bank_mask:0xf
	s_nop 1
	v_add_f32_dpp v5, v5, v5 row_half_mirror row_mask:0xf bank_mask:0xf
	s_nop 1
	v_add_f32_dpp v5, v5, v5 row_mirror row_mask:0xf bank_mask:0xf
	s_nop 1
	v_add_f32_dpp v5, v5, v5 row_bcast:15 row_mask:0xa bank_mask:0xf
	s_nop 1
	v_add_f32_dpp v5, v5, v5 row_bcast:31 row_mask:0xc bank_mask:0xf
	s_nop 1
	v_readlane_b32 s32, v5, 63
	s_nop 1
	v_mov_b32_e32 v6, s32
	v_fmamk_f32 v6, v6, 0x3a800000, v146
	v_rsq_f32_e32 v6, v6
	s_nop 0
	v_mov_b32_e32 v10, v6
	v_pk_mul_f32 v[14:15], v[86:87], v[10:11] op_sel_hi:[1,0]
	v_pk_mul_f32 v[14:15], v[54:55], v[14:15]
	v_pk_fma_f32 v[16:17], v[38:39], v[14:15], v[22:23]
	v_pk_mul_f32 v[14:15], v[88:89], v[10:11] op_sel_hi:[1,0]
	v_pk_mul_f32 v[14:15], v[56:57], v[14:15]
	v_pk_fma_f32 v[18:19], v[40:41], v[14:15], v[24:25]
	v_cvt_pk_bf16_f32 v118, v16, v17
	v_cvt_pk_bf16_f32 v119, v18, v19
	v_pk_mul_f32 v[14:15], v[90:91], v[10:11] op_sel_hi:[1,0]
	v_pk_mul_f32 v[14:15], v[58:59], v[14:15]
	v_pk_fma_f32 v[16:17], v[42:43], v[14:15], v[26:27]
	v_pk_mul_f32 v[14:15], v[92:93], v[10:11] op_sel_hi:[1,0]
	v_pk_mul_f32 v[14:15], v[60:61], v[14:15]
	v_pk_fma_f32 v[18:19], v[44:45], v[14:15], v[28:29]
	v_cvt_pk_bf16_f32 v120, v16, v17
	v_cvt_pk_bf16_f32 v121, v18, v19
	v_pk_mul_f32 v[14:15], v[94:95], v[10:11] op_sel_hi:[1,0]
	v_pk_mul_f32 v[14:15], v[62:63], v[14:15]
	v_pk_fma_f32 v[16:17], v[46:47], v[14:15], v[30:31]
	v_pk_mul_f32 v[14:15], v[96:97], v[10:11] op_sel_hi:[1,0]
	v_pk_mul_f32 v[14:15], v[64:65], v[14:15]
	v_pk_fma_f32 v[18:19], v[48:49], v[14:15], v[32:33]
	v_cvt_pk_bf16_f32 v122, v16, v17
	v_cvt_pk_bf16_f32 v123, v18, v19
	v_pk_mul_f32 v[14:15], v[98:99], v[10:11] op_sel_hi:[1,0]
	v_pk_mul_f32 v[14:15], v[66:67], v[14:15]
	v_pk_fma_f32 v[16:17], v[50:51], v[14:15], v[34:35]
	v_pk_mul_f32 v[14:15], v[100:101], v[10:11] op_sel_hi:[1,0]
	v_pk_mul_f32 v[14:15], v[68:69], v[14:15]
	v_pk_fma_f32 v[18:19], v[52:53], v[14:15], v[36:37]
	v_cvt_pk_bf16_f32 v124, v16, v17
	v_cvt_pk_bf16_f32 v125, v18, v19
	global_store_dwordx2 v1, v[118:119], s[62:63] offset:0 sc1
	global_store_dwordx2 v1, v[120:121], s[62:63] offset:512 sc1
	global_store_dwordx2 v1, v[122:123], s[62:63] offset:1024 sc1
	global_store_dwordx2 v1, v[124:125], s[62:63] offset:1536 sc1
	global_store_dwordx4 v0, v[86:89], s[46:47] offset:0
	global_store_dwordx4 v0, v[90:93], s[46:47] offset:1024
	global_store_dwordx4 v0, v[94:97], s[46:47] offset:2048
	global_store_dwordx4 v0, v[98:101], s[46:47] offset:3072
	s_add_u32 s46, s46, 0x1000
	s_addc_u32 s47, s47, 0
	s_add_u32 s62, s62, 0x800
	s_addc_u32 s63, s63, 0
	s_waitcnt vmcnt(20)
	v_pk_mul_f32 v[12:13], v[102:103], v[102:103]
	v_pk_fma_f32 v[12:13], v[104:105], v[104:105], v[12:13]
	v_pk_fma_f32 v[12:13], v[106:107], v[106:107], v[12:13]
	v_pk_fma_f32 v[12:13], v[108:109], v[108:109], v[12:13]
	v_pk_fma_f32 v[12:13], v[110:111], v[110:111], v[12:13]
	v_pk_fma_f32 v[12:13], v[112:113], v[112:113], v[12:13]
	v_pk_fma_f32 v[12:13], v[114:115], v[114:115], v[12:13]
	v_pk_fma_f32 v[12:13], v[116:117], v[116:117], v[12:13]
	v_add_f32_e32 v5, v12, v13
	s_nop 1
	v_add_f32_dpp v5, v5, v5 quad_perm:[1,0,3,2] row_mask:0xf bank_mask:0xf
	s_nop 1
	v_add_f32_dpp v5, v5, v5 quad_perm:[2,3,0,1] row_mask:0xf bank_mask:0xf
	s_nop 1
	v_add_f32_dpp v5, v5, v5 row_half_mirror row_mask:0xf bank_mask:0xf
	s_nop 1
	v_add_f32_dpp v5, v5, v5 row_mirror row_mask:0xf bank_mask:0xf
	s_nop 1
	v_add_f32_dpp v5, v5, v5 row_bcast:15 row_mask:0xa bank_mask:0xf
	s_nop 1
	v_add_f32_dpp v5, v5, v5 row_bcast:31 row_mask:0xc bank_mask:0xf
	s_nop 1
	v_readlane_b32 s32, v5, 63
	s_nop 1
	v_mov_b32_e32 v6, s32
	v_fmamk_f32 v6, v6, 0x3a800000, v146
	v_rsq_f32_e32 v6, v6
	s_nop 0
	v_mov_b32_e32 v10, v6
	v_pk_mul_f32 v[14:15], v[102:103], v[10:11] op_sel_hi:[1,0]
	v_pk_mul_f32 v[14:15], v[54:55], v[14:15]
	v_pk_fma_f32 v[16:17], v[38:39], v[14:15], v[22:23]
	v_pk_mul_f32 v[14:15], v[104:105], v[10:11] op_sel_hi:[1,0]
	v_pk_mul_f32 v[14:15], v[56:57], v[14:15]
	v_pk_fma_f32 v[18:19], v[40:41], v[14:15], v[24:25]
	v_cvt_pk_bf16_f32 v118, v16, v17
	v_cvt_pk_bf16_f32 v119, v18, v19
	v_pk_mul_f32 v[14:15], v[106:107], v[10:11] op_sel_hi:[1,0]
	v_pk_mul_f32 v[14:15], v[58:59], v[14:15]
	v_pk_fma_f32 v[16:17], v[42:43], v[14:15], v[26:27]
	v_pk_mul_f32 v[14:15], v[108:109], v[10:11] op_sel_hi:[1,0]
	v_pk_mul_f32 v[14:15], v[60:61], v[14:15]
	v_pk_fma_f32 v[18:19], v[44:45], v[14:15], v[28:29]
	v_cvt_pk_bf16_f32 v120, v16, v17
	v_cvt_pk_bf16_f32 v121, v18, v19
	v_pk_mul_f32 v[14:15], v[110:111], v[10:11] op_sel_hi:[1,0]
	v_pk_mul_f32 v[14:15], v[62:63], v[14:15]
	v_pk_fma_f32 v[16:17], v[46:47], v[14:15], v[30:31]
	v_pk_mul_f32 v[14:15], v[112:113], v[10:11] op_sel_hi:[1,0]
	v_pk_mul_f32 v[14:15], v[64:65], v[14:15]
	v_pk_fma_f32 v[18:19], v[48:49], v[14:15], v[32:33]
	v_cvt_pk_bf16_f32 v122, v16, v17
	v_cvt_pk_bf16_f32 v123, v18, v19
	v_pk_mul_f32 v[14:15], v[114:115], v[10:11] op_sel_hi:[1,0]
	v_pk_mul_f32 v[14:15], v[66:67], v[14:15]
	v_pk_fma_f32 v[16:17], v[50:51], v[14:15], v[34:35]
	v_pk_mul_f32 v[14:15], v[116:117], v[10:11] op_sel_hi:[1,0]
	v_pk_mul_f32 v[14:15], v[68:69], v[14:15]
	v_pk_fma_f32 v[18:19], v[52:53], v[14:15], v[36:37]
	v_cvt_pk_bf16_f32 v124, v16, v17
	v_cvt_pk_bf16_f32 v125, v18, v19
	global_store_dwordx2 v1, v[118:119], s[62:63] offset:0 sc1
	global_store_dwordx2 v1, v[120:121], s[62:63] offset:512 sc1
	global_store_dwordx2 v1, v[122:123], s[62:63] offset:1024 sc1
	global_store_dwordx2 v1, v[124:125], s[62:63] offset:1536 sc1
	global_store_dwordx4 v0, v[102:105], s[46:47] offset:0
	global_store_dwordx4 v0, v[106:109], s[46:47] offset:1024
	global_store_dwordx4 v0, v[110:113], s[46:47] offset:2048
	global_store_dwordx4 v0, v[114:117], s[46:47] offset:3072
	s_add_u32 s46, s46, 0x1000
	s_addc_u32 s47, s47, 0
	s_add_u32 s62, s62, 0x800
	s_addc_u32 s63, s63, 0
	s_waitcnt vmcnt(16)
	v_pk_mul_f32 v[12:13], v[70:71], v[70:71]
	v_pk_fma_f32 v[12:13], v[72:73], v[72:73], v[12:13]
	v_pk_fma_f32 v[12:13], v[74:75], v[74:75], v[12:13]
	v_pk_fma_f32 v[12:13], v[76:77], v[76:77], v[12:13]
	v_pk_fma_f32 v[12:13], v[78:79], v[78:79], v[12:13]
	v_pk_fma_f32 v[12:13], v[80:81], v[80:81], v[12:13]
	v_pk_fma_f32 v[12:13], v[82:83], v[82:83], v[12:13]
	v_pk_fma_f32 v[12:13], v[84:85], v[84:85], v[12:13]
	v_add_f32_e32 v5, v12, v13
	s_nop 1
	v_add_f32_dpp v5, v5, v5 quad_perm:[1,0,3,2] row_mask:0xf bank_mask:0xf
	s_nop 1
	v_add_f32_dpp v5, v5, v5 quad_perm:[2,3,0,1] row_mask:0xf bank_mask:0xf
	s_nop 1
	v_add_f32_dpp v5, v5, v5 row_half_mirror row_mask:0xf bank_mask:0xf
	s_nop 1
	v_add_f32_dpp v5, v5, v5 row_mirror row_mask:0xf bank_mask:0xf
	s_nop 1
	v_add_f32_dpp v5, v5, v5 row_bcast:15 row_mask:0xa bank_mask:0xf
	s_nop 1
	v_add_f32_dpp v5, v5, v5 row_bcast:31 row_mask:0xc bank_mask:0xf
	s_nop 1
	v_readlane_b32 s32, v5, 63
	s_nop 1
	v_mov_b32_e32 v6, s32
	v_fmamk_f32 v6, v6, 0x3a800000, v146
	v_rsq_f32_e32 v6, v6
	s_nop 0
	v_mov_b32_e32 v10, v6
	v_pk_mul_f32 v[14:15], v[70:71], v[10:11] op_sel_hi:[1,0]
	v_pk_mul_f32 v[14:15], v[54:55], v[14:15]
	v_pk_fma_f32 v[16:17], v[38:39], v[14:15], v[22:23]
	v_pk_mul_f32 v[14:15], v[72:73], v[10:11] op_sel_hi:[1,0]
	v_pk_mul_f32 v[14:15], v[56:57], v[14:15]
	v_pk_fma_f32 v[18:19], v[40:41], v[14:15], v[24:25]
	v_cvt_pk_bf16_f32 v118, v16, v17
	v_cvt_pk_bf16_f32 v119, v18, v19
	v_pk_mul_f32 v[14:15], v[74:75], v[10:11] op_sel_hi:[1,0]
	v_pk_mul_f32 v[14:15], v[58:59], v[14:15]
	v_pk_fma_f32 v[16:17], v[42:43], v[14:15], v[26:27]
	v_pk_mul_f32 v[14:15], v[76:77], v[10:11] op_sel_hi:[1,0]
	v_pk_mul_f32 v[14:15], v[60:61], v[14:15]
	v_pk_fma_f32 v[18:19], v[44:45], v[14:15], v[28:29]
	v_cvt_pk_bf16_f32 v120, v16, v17
	v_cvt_pk_bf16_f32 v121, v18, v19
	v_pk_mul_f32 v[14:15], v[78:79], v[10:11] op_sel_hi:[1,0]
	v_pk_mul_f32 v[14:15], v[62:63], v[14:15]
	v_pk_fma_f32 v[16:17], v[46:47], v[14:15], v[30:31]
	v_pk_mul_f32 v[14:15], v[80:81], v[10:11] op_sel_hi:[1,0]
	v_pk_mul_f32 v[14:15], v[64:65], v[14:15]
	v_pk_fma_f32 v[18:19], v[48:49], v[14:15], v[32:33]
	v_cvt_pk_bf16_f32 v122, v16, v17
	v_cvt_pk_bf16_f32 v123, v18, v19
	v_pk_mul_f32 v[14:15], v[82:83], v[10:11] op_sel_hi:[1,0]
	v_pk_mul_f32 v[14:15], v[66:67], v[14:15]
	v_pk_fma_f32 v[16:17], v[50:51], v[14:15], v[34:35]
	v_pk_mul_f32 v[14:15], v[84:85], v[10:11] op_sel_hi:[1,0]
	v_pk_mul_f32 v[14:15], v[68:69], v[14:15]
	v_pk_fma_f32 v[18:19], v[52:53], v[14:15], v[36:37]
	v_cvt_pk_bf16_f32 v124, v16, v17
	v_cvt_pk_bf16_f32 v125, v18, v19
	global_store_dwordx2 v1, v[118:119], s[62:63] offset:0 sc1
	global_store_dwordx2 v1, v[120:121], s[62:63] offset:512 sc1
	global_store_dwordx2 v1, v[122:123], s[62:63] offset:1024 sc1
	global_store_dwordx2 v1, v[124:125], s[62:63] offset:1536 sc1
	global_store_dwordx4 v0, v[70:73], s[46:47] offset:0
	global_store_dwordx4 v0, v[74:77], s[46:47] offset:1024
	global_store_dwordx4 v0, v[78:81], s[46:47] offset:2048
	global_store_dwordx4 v0, v[82:85], s[46:47] offset:3072
	s_add_u32 s46, s46, 0x1000
	s_addc_u32 s47, s47, 0
	s_add_u32 s62, s62, 0x800
	s_addc_u32 s63, s63, 0

.Lnw_skip_n1:
	s_or_b64 exec, exec, s[40:41]
	s_barrier
	global_load_dwordx2 v[86:87], v1, s[58:59] offset:0
	global_load_dwordx2 v[90:91], v1, s[58:59] offset:512
	global_load_dwordx2 v[94:95], v1, s[58:59] offset:1024
	global_load_dwordx2 v[98:99], v1, s[58:59] offset:1536
	global_load_dwordx2 v[88:89], v1, s[60:61] offset:0
	global_load_dwordx2 v[92:93], v1, s[60:61] offset:512
	global_load_dwordx2 v[96:97], v1, s[60:61] offset:1024
	global_load_dwordx2 v[100:101], v1, s[60:61] offset:1536
	s_add_u32 s58, s58, 0x800
	s_addc_u32 s59, s59, 0
	s_add_u32 s60, s60, 0x800
	s_addc_u32 s61, s61, 0
	global_load_dwordx2 v[118:119], v1, s[58:59] offset:0
	global_load_dwordx2 v[122:123], v1, s[58:59] offset:512
	global_load_dwordx2 v[134:135], v1, s[58:59] offset:1024
	global_load_dwordx2 v[138:139], v1, s[58:59] offset:1536
	global_load_dwordx2 v[120:121], v1, s[60:61] offset:0
	global_load_dwordx2 v[124:125], v1, s[60:61] offset:512
	global_load_dwordx2 v[136:137], v1, s[60:61] offset:1024
	global_load_dwordx2 v[140:141], v1, s[60:61] offset:1536
	s_add_u32 s58, s58, 0x800
	s_addc_u32 s59, s59, 0
	s_add_u32 s60, s60, 0x800
	s_addc_u32 s61, s61, 0
	global_load_dwordx2 v[172:173], v1, s[58:59] offset:0
	global_load_dwordx2 v[176:177], v1, s[58:59] offset:512
	global_load_dwordx2 v[204:205], v1, s[58:59] offset:1024
	global_load_dwordx2 v[214:215], v1, s[58:59] offset:1536
	global_load_dwordx2 v[174:175], v1, s[60:61] offset:0
	global_load_dwordx2 v[178:179], v1, s[60:61] offset:512
	global_load_dwordx2 v[206:207], v1, s[60:61] offset:1024
	global_load_dwordx2 v[216:217], v1, s[60:61] offset:1536
	s_add_u32 s58, s58, 0x800
	s_addc_u32 s59, s59, 0
	s_add_u32 s60, s60, 0x800
	s_addc_u32 s61, s61, 0
	global_load_dwordx2 v[234:235], v1, s[58:59] offset:0
	global_load_dwordx2 v[238:239], v1, s[58:59] offset:512
	global_load_dwordx2 v[242:243], v1, s[58:59] offset:1024
	global_load_dwordx2 v[246:247], v1, s[58:59] offset:1536
	global_load_dwordx2 v[236:237], v1, s[60:61] offset:0
	global_load_dwordx2 v[240:241], v1, s[60:61] offset:512
	global_load_dwordx2 v[244:245], v1, s[60:61] offset:1024
	global_load_dwordx2 v[248:249], v1, s[60:61] offset:1536
	s_add_u32 s58, s58, 0x800
	s_addc_u32 s59, s59, 0
	s_add_u32 s60, s60, 0x800
	s_addc_u32 s61, s61, 0
	s_waitcnt vmcnt(24)
	v_lshlrev_b32_e32 v14, 16, v86
	v_and_b32_e32 v15, 0xffff0000, v86
	v_lshlrev_b32_e32 v16, 16, v88
	v_and_b32_e32 v17, 0xffff0000, v88
	v_lshlrev_b32_e32 v18, 16, v87
	v_and_b32_e32 v19, 0xffff0000, v87
	v_lshlrev_b32_e32 v20, 16, v89
	v_and_b32_e32 v21, 0xffff0000, v89
	v_pk_add_f32 v[86:87], v[14:15], v[16:17]
	v_pk_add_f32 v[88:89], v[18:19], v[20:21]
	v_lshlrev_b32_e32 v14, 16, v90
	v_and_b32_e32 v15, 0xffff0000, v90
	v_lshlrev_b32_e32 v16, 16, v92
	v_and_b32_e32 v17, 0xffff0000, v92
	v_lshlrev_b32_e32 v18, 16, v91
	v_and_b32_e32 v19, 0xffff0000, v91
	v_lshlrev_b32_e32 v20, 16, v93
	v_and_b32_e32 v21, 0xffff0000, v93
	v_pk_add_f32 v[90:91], v[14:15], v[16:17]
	v_pk_add_f32 v[92:93], v[18:19], v[20:21]
	v_lshlrev_b32_e32 v14, 16, v94
	v_and_b32_e32 v15, 0xffff0000, v94
	v_lshlrev_b32_e32 v16, 16, v96
	v_and_b32_e32 v17, 0xffff0000, v96
	v_lshlrev_b32_e32 v18, 16, v95
	v_and_b32_e32 v19, 0xffff0000, v95
	v_lshlrev_b32_e32 v20, 16, v97
	v_and_b32_e32 v21, 0xffff0000, v97
	v_pk_add_f32 v[94:95], v[14:15], v[16:17]
	v_pk_add_f32 v[96:97], v[18:19], v[20:21]
	v_lshlrev_b32_e32 v14, 16, v98
	v_and_b32_e32 v15, 0xffff0000, v98
	v_lshlrev_b32_e32 v16, 16, v100
	v_and_b32_e32 v17, 0xffff0000, v100
	v_lshlrev_b32_e32 v18, 16, v99
	v_and_b32_e32 v19, 0xffff0000, v99
	v_lshlrev_b32_e32 v20, 16, v101
	v_and_b32_e32 v21, 0xffff0000, v101
	v_pk_add_f32 v[98:99], v[14:15], v[16:17]
	v_pk_add_f32 v[100:101], v[18:19], v[20:21]
	v_pk_mul_f32 v[12:13], v[86:87], v[86:87]
	v_pk_fma_f32 v[12:13], v[88:89], v[88:89], v[12:13]
	v_pk_fma_f32 v[12:13], v[90:91], v[90:91], v[12:13]
	v_pk_fma_f32 v[12:13], v[92:93], v[92:93], v[12:13]
	v_pk_fma_f32 v[12:13], v[94:95], v[94:95], v[12:13]
	v_pk_fma_f32 v[12:13], v[96:97], v[96:97], v[12:13]
	v_pk_fma_f32 v[12:13], v[98:99], v[98:99], v[12:13]
	v_pk_fma_f32 v[12:13], v[100:101], v[100:101], v[12:13]
	v_add_f32_e32 v5, v12, v13
	s_nop 1
	v_add_f32_dpp v5, v5, v5 quad_perm:[1,0,3,2] row_mask:0xf bank_mask:0xf
	s_nop 1
	v_add_f32_dpp v5, v5, v5 quad_perm:[2,3,0,1] row_mask:0xf bank_mask:0xf
	s_nop 1
	v_add_f32_dpp v5, v5, v5 row_half_mirror row_mask:0xf bank_mask:0xf
	s_nop 1
	v_add_f32_dpp v5, v5, v5 row_mirror row_mask:0xf bank_mask:0xf
	s_nop 1
	v_add_f32_dpp v5, v5, v5 row_bcast:15 row_mask:0xa bank_mask:0xf
	s_nop 1
	v_add_f32_dpp v5, v5, v5 row_bcast:31 row_mask:0xc bank_mask:0xf
	s_nop 1
	v_readlane_b32 s32, v5, 63
	s_nop 1
	v_mov_b32_e32 v6, s32
	v_fmamk_f32 v6, v6, 0x3a800000, v146
	v_rsq_f32_e32 v6, v6
	s_nop 0
	v_mul_f32_e32 v8, 0.5, v6
	v_pk_mul_f32 v[14:15], v[86:87], v[8:9] op_sel_hi:[1,0]
	v_pk_fma_f32 v[70:71], v[22:23], v[14:15], v[70:71]
	v_pk_mul_f32 v[14:15], v[88:89], v[8:9] op_sel_hi:[1,0]
	v_pk_fma_f32 v[72:73], v[24:25], v[14:15], v[72:73]
	v_pk_mul_f32 v[14:15], v[90:91], v[8:9] op_sel_hi:[1,0]
	v_pk_fma_f32 v[74:75], v[26:27], v[14:15], v[74:75]
	v_pk_mul_f32 v[14:15], v[92:93], v[8:9] op_sel_hi:[1,0]
	v_pk_fma_f32 v[76:77], v[28:29], v[14:15], v[76:77]
	v_pk_mul_f32 v[14:15], v[94:95], v[8:9] op_sel_hi:[1,0]
	v_pk_fma_f32 v[78:79], v[30:31], v[14:15], v[78:79]
	v_pk_mul_f32 v[14:15], v[96:97], v[8:9] op_sel_hi:[1,0]
	v_pk_fma_f32 v[80:81], v[32:33], v[14:15], v[80:81]
	v_pk_mul_f32 v[14:15], v[98:99], v[8:9] op_sel_hi:[1,0]
	v_pk_fma_f32 v[82:83], v[34:35], v[14:15], v[82:83]
	v_pk_mul_f32 v[14:15], v[100:101], v[8:9] op_sel_hi:[1,0]
	v_pk_fma_f32 v[84:85], v[36:37], v[14:15], v[84:85]
	v_pk_mul_f32 v[12:13], v[70:71], v[70:71]
	v_pk_fma_f32 v[12:13], v[72:73], v[72:73], v[12:13]
	v_pk_fma_f32 v[12:13], v[74:75], v[74:75], v[12:13]
	v_pk_fma_f32 v[12:13], v[76:77], v[76:77], v[12:13]
	v_pk_fma_f32 v[12:13], v[78:79], v[78:79], v[12:13]
	v_pk_fma_f32 v[12:13], v[80:81], v[80:81], v[12:13]
	v_pk_fma_f32 v[12:13], v[82:83], v[82:83], v[12:13]
	v_pk_fma_f32 v[12:13], v[84:85], v[84:85], v[12:13]
	v_add_f32_e32 v5, v12, v13
	s_nop 1
	v_add_f32_dpp v5, v5, v5 quad_perm:[1,0,3,2] row_mask:0xf bank_mask:0xf
	s_nop 1
	v_add_f32_dpp v5, v5, v5 quad_perm:[2,3,0,1] row_mask:0xf bank_mask:0xf
	s_nop 1
	v_add_f32_dpp v5, v5, v5 row_half_mirror row_mask:0xf bank_mask:0xf
	s_nop 1
	v_add_f32_dpp v5, v5, v5 row_mirror row_mask:0xf bank_mask:0xf
	s_nop 1
	v_add_f32_dpp v5, v5, v5 row_bcast:15 row_mask:0xa bank_mask:0xf
	s_nop 1
	v_add_f32_dpp v5, v5, v5 row_bcast:31 row_mask:0xc bank_mask:0xf
	s_nop 1
	v_readlane_b32 s32, v5, 63
	s_nop 1
	v_mov_b32_e32 v6, s32
	v_fmamk_f32 v6, v6, 0x3a800000, v146
	v_rsq_f32_e32 v6, v6
	s_nop 0
	v_mov_b32_e32 v10, v6
	v_pk_mul_f32 v[14:15], v[70:71], v[10:11] op_sel_hi:[1,0]
	v_pk_fma_f32 v[16:17], v[54:55], v[14:15], v[38:39]
	v_pk_mul_f32 v[14:15], v[72:73], v[10:11] op_sel_hi:[1,0]
	v_pk_fma_f32 v[18:19], v[56:57], v[14:15], v[40:41]
	v_cvt_pk_bf16_f32 v86, v16, v17
	v_cvt_pk_bf16_f32 v87, v18, v19
	v_pk_mul_f32 v[14:15], v[74:75], v[10:11] op_sel_hi:[1,0]
	v_pk_fma_f32 v[16:17], v[58:59], v[14:15], v[42:43]
	v_pk_mul_f32 v[14:15], v[76:77], v[10:11] op_sel_hi:[1,0]
	v_pk_fma_f32 v[18:19], v[60:61], v[14:15], v[44:45]
	v_cvt_pk_bf16_f32 v90, v16, v17
	v_cvt_pk_bf16_f32 v91, v18, v19
	v_pk_mul_f32 v[14:15], v[78:79], v[10:11] op_sel_hi:[1,0]
	v_pk_fma_f32 v[16:17], v[62:63], v[14:15], v[46:47]
	v_pk_mul_f32 v[14:15], v[80:81], v[10:11] op_sel_hi:[1,0]
	v_pk_fma_f32 v[18:19], v[64:65], v[14:15], v[48:49]
	v_cvt_pk_bf16_f32 v94, v16, v17
	v_cvt_pk_bf16_f32 v95, v18, v19
	v_pk_mul_f32 v[14:15], v[82:83], v[10:11] op_sel_hi:[1,0]
	v_pk_fma_f32 v[16:17], v[66:67], v[14:15], v[50:51]
	v_pk_mul_f32 v[14:15], v[84:85], v[10:11] op_sel_hi:[1,0]
	v_pk_fma_f32 v[18:19], v[68:69], v[14:15], v[52:53]
	v_cvt_pk_bf16_f32 v98, v16, v17
	v_cvt_pk_bf16_f32 v99, v18, v19
	global_store_dwordx2 v1, v[86:87], s[62:63] offset:0 sc1
	global_store_dwordx2 v1, v[90:91], s[62:63] offset:512 sc1
	global_store_dwordx2 v1, v[94:95], s[62:63] offset:1024 sc1
	global_store_dwordx2 v1, v[98:99], s[62:63] offset:1536 sc1
	global_store_dwordx4 v0, v[70:73], s[46:47] offset:0
	global_store_dwordx4 v0, v[74:77], s[46:47] offset:1024
	global_store_dwordx4 v0, v[78:81], s[46:47] offset:2048
	global_store_dwordx4 v0, v[82:85], s[46:47] offset:3072
	s_add_u32 s46, s46, 0x1000
	s_addc_u32 s47, s47, 0
	s_add_u32 s62, s62, 0x800
	s_addc_u32 s63, s63, 0
	s_waitcnt vmcnt(24)
	v_lshlrev_b32_e32 v14, 16, v118
	v_and_b32_e32 v15, 0xffff0000, v118
	v_lshlrev_b32_e32 v16, 16, v120
	v_and_b32_e32 v17, 0xffff0000, v120
	v_lshlrev_b32_e32 v18, 16, v119
	v_and_b32_e32 v19, 0xffff0000, v119
	v_lshlrev_b32_e32 v20, 16, v121
	v_and_b32_e32 v21, 0xffff0000, v121
	v_pk_add_f32 v[118:119], v[14:15], v[16:17]
	v_pk_add_f32 v[120:121], v[18:19], v[20:21]
	v_lshlrev_b32_e32 v14, 16, v122
	v_and_b32_e32 v15, 0xffff0000, v122
	v_lshlrev_b32_e32 v16, 16, v124
	v_and_b32_e32 v17, 0xffff0000, v124
	v_lshlrev_b32_e32 v18, 16, v123
	v_and_b32_e32 v19, 0xffff0000, v123
	v_lshlrev_b32_e32 v20, 16, v125
	v_and_b32_e32 v21, 0xffff0000, v125
	v_pk_add_f32 v[122:123], v[14:15], v[16:17]
	v_pk_add_f32 v[124:125], v[18:19], v[20:21]
	v_lshlrev_b32_e32 v14, 16, v134
	v_and_b32_e32 v15, 0xffff0000, v134
	v_lshlrev_b32_e32 v16, 16, v136
	v_and_b32_e32 v17, 0xffff0000, v136
	v_lshlrev_b32_e32 v18, 16, v135
	v_and_b32_e32 v19, 0xffff0000, v135
	v_lshlrev_b32_e32 v20, 16, v137
	v_and_b32_e32 v21, 0xffff0000, v137
	v_pk_add_f32 v[134:135], v[14:15], v[16:17]
	v_pk_add_f32 v[136:137], v[18:19], v[20:21]
	v_lshlrev_b32_e32 v14, 16, v138
	v_and_b32_e32 v15, 0xffff0000, v138
	v_lshlrev_b32_e32 v16, 16, v140
	v_and_b32_e32 v17, 0xffff0000, v140
	v_lshlrev_b32_e32 v18, 16, v139
	v_and_b32_e32 v19, 0xffff0000, v139
	v_lshlrev_b32_e32 v20, 16, v141
	v_and_b32_e32 v21, 0xffff0000, v141
	v_pk_add_f32 v[138:139], v[14:15], v[16:17]
	v_pk_add_f32 v[140:141], v[18:19], v[20:21]
	v_pk_mul_f32 v[12:13], v[118:119], v[118:119]
	v_pk_fma_f32 v[12:13], v[120:121], v[120:121], v[12:13]
	v_pk_fma_f32 v[12:13], v[122:123], v[122:123], v[12:13]
	v_pk_fma_f32 v[12:13], v[124:125], v[124:125], v[12:13]
	v_pk_fma_f32 v[12:13], v[134:135], v[134:135], v[12:13]
	v_pk_fma_f32 v[12:13], v[136:137], v[136:137], v[12:13]
	v_pk_fma_f32 v[12:13], v[138:139], v[138:139], v[12:13]
	v_pk_fma_f32 v[12:13], v[140:141], v[140:141], v[12:13]
	v_add_f32_e32 v5, v12, v13
	s_nop 1
	v_add_f32_dpp v5, v5, v5 quad_perm:[1,0,3,2] row_mask:0xf bank_mask:0xf
	s_nop 1
	v_add_f32_dpp v5, v5, v5 quad_perm:[2,3,0,1] row_mask:0xf bank_mask:0xf
	s_nop 1
	v_add_f32_dpp v5, v5, v5 row_half_mirror row_mask:0xf bank_mask:0xf
	s_nop 1
	v_add_f32_dpp v5, v5, v5 row_mirror row_mask:0xf bank_mask:0xf
	s_nop 1
	v_add_f32_dpp v5, v5, v5 row_bcast:15 row_mask:0xa bank_mask:0xf
	s_nop 1
	v_add_f32_dpp v5, v5, v5 row_bcast:31 row_mask:0xc bank_mask:0xf
	s_nop 1
	v_readlane_b32 s32, v5, 63
	s_nop 1
	v_mov_b32_e32 v6, s32
	v_fmamk_f32 v6, v6, 0x3a800000, v146
	v_rsq_f32_e32 v6, v6
	s_nop 0
	v_mul_f32_e32 v8, 0.5, v6
	v_pk_mul_f32 v[14:15], v[118:119], v[8:9] op_sel_hi:[1,0]
	v_pk_fma_f32 v[102:103], v[22:23], v[14:15], v[102:103]
	v_pk_mul_f32 v[14:15], v[120:121], v[8:9] op_sel_hi:[1,0]
	v_pk_fma_f32 v[104:105], v[24:25], v[14:15], v[104:105]
	v_pk_mul_f32 v[14:15], v[122:123], v[8:9] op_sel_hi:[1,0]
	v_pk_fma_f32 v[106:107], v[26:27], v[14:15], v[106:107]
	v_pk_mul_f32 v[14:15], v[124:125], v[8:9] op_sel_hi:[1,0]
	v_pk_fma_f32 v[108:109], v[28:29], v[14:15], v[108:109]
	v_pk_mul_f32 v[14:15], v[134:135], v[8:9] op_sel_hi:[1,0]
	v_pk_fma_f32 v[110:111], v[30:31], v[14:15], v[110:111]
	v_pk_mul_f32 v[14:15], v[136:137], v[8:9] op_sel_hi:[1,0]
	v_pk_fma_f32 v[112:113], v[32:33], v[14:15], v[112:113]
	v_pk_mul_f32 v[14:15], v[138:139], v[8:9] op_sel_hi:[1,0]
	v_pk_fma_f32 v[114:115], v[34:35], v[14:15], v[114:115]
	v_pk_mul_f32 v[14:15], v[140:141], v[8:9] op_sel_hi:[1,0]
	v_pk_fma_f32 v[116:117], v[36:37], v[14:15], v[116:117]
	v_pk_mul_f32 v[12:13], v[102:103], v[102:103]
	v_pk_fma_f32 v[12:13], v[104:105], v[104:105], v[12:13]
	v_pk_fma_f32 v[12:13], v[106:107], v[106:107], v[12:13]
	v_pk_fma_f32 v[12:13], v[108:109], v[108:109], v[12:13]
	v_pk_fma_f32 v[12:13], v[110:111], v[110:111], v[12:13]
	v_pk_fma_f32 v[12:13], v[112:113], v[112:113], v[12:13]
	v_pk_fma_f32 v[12:13], v[114:115], v[114:115], v[12:13]
	v_pk_fma_f32 v[12:13], v[116:117], v[116:117], v[12:13]
	v_add_f32_e32 v5, v12, v13
	s_nop 1
	v_add_f32_dpp v5, v5, v5 quad_perm:[1,0,3,2] row_mask:0xf bank_mask:0xf
	s_nop 1
	v_add_f32_dpp v5, v5, v5 quad_perm:[2,3,0,1] row_mask:0xf bank_mask:0xf
	s_nop 1
	v_add_f32_dpp v5, v5, v5 row_half_mirror row_mask:0xf bank_mask:0xf
	s_nop 1
	v_add_f32_dpp v5, v5, v5 row_mirror row_mask:0xf bank_mask:0xf
	s_nop 1
	v_add_f32_dpp v5, v5, v5 row_bcast:15 row_mask:0xa bank_mask:0xf
	s_nop 1
	v_add_f32_dpp v5, v5, v5 row_bcast:31 row_mask:0xc bank_mask:0xf
	s_nop 1
	v_readlane_b32 s32, v5, 63
	s_nop 1
	v_mov_b32_e32 v6, s32
	v_fmamk_f32 v6, v6, 0x3a800000, v146
	v_rsq_f32_e32 v6, v6
	s_nop 0
	v_mov_b32_e32 v10, v6
	v_pk_mul_f32 v[14:15], v[102:103], v[10:11] op_sel_hi:[1,0]
	v_pk_fma_f32 v[16:17], v[54:55], v[14:15], v[38:39]
	v_pk_mul_f32 v[14:15], v[104:105], v[10:11] op_sel_hi:[1,0]
	v_pk_fma_f32 v[18:19], v[56:57], v[14:15], v[40:41]
	v_cvt_pk_bf16_f32 v118, v16, v17
	v_cvt_pk_bf16_f32 v119, v18, v19
	v_pk_mul_f32 v[14:15], v[106:107], v[10:11] op_sel_hi:[1,0]
	v_pk_fma_f32 v[16:17], v[58:59], v[14:15], v[42:43]
	v_pk_mul_f32 v[14:15], v[108:109], v[10:11] op_sel_hi:[1,0]
	v_pk_fma_f32 v[18:19], v[60:61], v[14:15], v[44:45]
	v_cvt_pk_bf16_f32 v122, v16, v17
	v_cvt_pk_bf16_f32 v123, v18, v19
	v_pk_mul_f32 v[14:15], v[110:111], v[10:11] op_sel_hi:[1,0]
	v_pk_fma_f32 v[16:17], v[62:63], v[14:15], v[46:47]
	v_pk_mul_f32 v[14:15], v[112:113], v[10:11] op_sel_hi:[1,0]
	v_pk_fma_f32 v[18:19], v[64:65], v[14:15], v[48:49]
	v_cvt_pk_bf16_f32 v134, v16, v17
	v_cvt_pk_bf16_f32 v135, v18, v19
	v_pk_mul_f32 v[14:15], v[114:115], v[10:11] op_sel_hi:[1,0]
	v_pk_fma_f32 v[16:17], v[66:67], v[14:15], v[50:51]
	v_pk_mul_f32 v[14:15], v[116:117], v[10:11] op_sel_hi:[1,0]
	v_pk_fma_f32 v[18:19], v[68:69], v[14:15], v[52:53]
	v_cvt_pk_bf16_f32 v138, v16, v17
	v_cvt_pk_bf16_f32 v139, v18, v19
	global_store_dwordx2 v1, v[118:119], s[62:63] offset:0 sc1
	global_store_dwordx2 v1, v[122:123], s[62:63] offset:512 sc1
	global_store_dwordx2 v1, v[134:135], s[62:63] offset:1024 sc1
	global_store_dwordx2 v1, v[138:139], s[62:63] offset:1536 sc1
	global_store_dwordx4 v0, v[102:105], s[46:47] offset:0
	global_store_dwordx4 v0, v[106:109], s[46:47] offset:1024
	global_store_dwordx4 v0, v[110:113], s[46:47] offset:2048
	global_store_dwordx4 v0, v[114:117], s[46:47] offset:3072
	s_add_u32 s46, s46, 0x1000
	s_addc_u32 s47, s47, 0
	s_add_u32 s62, s62, 0x800
	s_addc_u32 s63, s63, 0
	s_waitcnt vmcnt(24)
	v_lshlrev_b32_e32 v14, 16, v172
	v_and_b32_e32 v15, 0xffff0000, v172
	v_lshlrev_b32_e32 v16, 16, v174
	v_and_b32_e32 v17, 0xffff0000, v174
	v_lshlrev_b32_e32 v18, 16, v173
	v_and_b32_e32 v19, 0xffff0000, v173
	v_lshlrev_b32_e32 v20, 16, v175
	v_and_b32_e32 v21, 0xffff0000, v175
	v_pk_add_f32 v[172:173], v[14:15], v[16:17]
	v_pk_add_f32 v[174:175], v[18:19], v[20:21]
	v_lshlrev_b32_e32 v14, 16, v176
	v_and_b32_e32 v15, 0xffff0000, v176
	v_lshlrev_b32_e32 v16, 16, v178
	v_and_b32_e32 v17, 0xffff0000, v178
	v_lshlrev_b32_e32 v18, 16, v177
	v_and_b32_e32 v19, 0xffff0000, v177
	v_lshlrev_b32_e32 v20, 16, v179
	v_and_b32_e32 v21, 0xffff0000, v179
	v_pk_add_f32 v[176:177], v[14:15], v[16:17]
	v_pk_add_f32 v[178:179], v[18:19], v[20:21]
	v_lshlrev_b32_e32 v14, 16, v204
	v_and_b32_e32 v15, 0xffff0000, v204
	v_lshlrev_b32_e32 v16, 16, v206
	v_and_b32_e32 v17, 0xffff0000, v206
	v_lshlrev_b32_e32 v18, 16, v205
	v_and_b32_e32 v19, 0xffff0000, v205
	v_lshlrev_b32_e32 v20, 16, v207
	v_and_b32_e32 v21, 0xffff0000, v207
	v_pk_add_f32 v[204:205], v[14:15], v[16:17]
	v_pk_add_f32 v[206:207], v[18:19], v[20:21]
	v_lshlrev_b32_e32 v14, 16, v214
	v_and_b32_e32 v15, 0xffff0000, v214
	v_lshlrev_b32_e32 v16, 16, v216
	v_and_b32_e32 v17, 0xffff0000, v216
	v_lshlrev_b32_e32 v18, 16, v215
	v_and_b32_e32 v19, 0xffff0000, v215
	v_lshlrev_b32_e32 v20, 16, v217
	v_and_b32_e32 v21, 0xffff0000, v217
	v_pk_add_f32 v[214:215], v[14:15], v[16:17]
	v_pk_add_f32 v[216:217], v[18:19], v[20:21]
	v_pk_mul_f32 v[12:13], v[172:173], v[172:173]
	v_pk_fma_f32 v[12:13], v[174:175], v[174:175], v[12:13]
	v_pk_fma_f32 v[12:13], v[176:177], v[176:177], v[12:13]
	v_pk_fma_f32 v[12:13], v[178:179], v[178:179], v[12:13]
	v_pk_fma_f32 v[12:13], v[204:205], v[204:205], v[12:13]
	v_pk_fma_f32 v[12:13], v[206:207], v[206:207], v[12:13]
	v_pk_fma_f32 v[12:13], v[214:215], v[214:215], v[12:13]
	v_pk_fma_f32 v[12:13], v[216:217], v[216:217], v[12:13]
	v_add_f32_e32 v5, v12, v13
	s_nop 1
	v_add_f32_dpp v5, v5, v5 quad_perm:[1,0,3,2] row_mask:0xf bank_mask:0xf
	s_nop 1
	v_add_f32_dpp v5, v5, v5 quad_perm:[2,3,0,1] row_mask:0xf bank_mask:0xf
	s_nop 1
	v_add_f32_dpp v5, v5, v5 row_half_mirror row_mask:0xf bank_mask:0xf
	s_nop 1
	v_add_f32_dpp v5, v5, v5 row_mirror row_mask:0xf bank_mask:0xf
	s_nop 1
	v_add_f32_dpp v5, v5, v5 row_bcast:15 row_mask:0xa bank_mask:0xf
	s_nop 1
	v_add_f32_dpp v5, v5, v5 row_bcast:31 row_mask:0xc bank_mask:0xf
	s_nop 1
	v_readlane_b32 s32, v5, 63
	s_nop 1
	v_mov_b32_e32 v6, s32
	v_fmamk_f32 v6, v6, 0x3a800000, v146
	v_rsq_f32_e32 v6, v6
	s_nop 0
	v_mul_f32_e32 v8, 0.5, v6
	v_pk_mul_f32 v[14:15], v[172:173], v[8:9] op_sel_hi:[1,0]
	v_pk_fma_f32 v[154:155], v[22:23], v[14:15], v[154:155]
	v_pk_mul_f32 v[14:15], v[174:175], v[8:9] op_sel_hi:[1,0]
	v_pk_fma_f32 v[156:157], v[24:25], v[14:15], v[156:157]
	v_pk_mul_f32 v[14:15], v[176:177], v[8:9] op_sel_hi:[1,0]
	v_pk_fma_f32 v[158:159], v[26:27], v[14:15], v[158:159]
	v_pk_mul_f32 v[14:15], v[178:179], v[8:9] op_sel_hi:[1,0]
	v_pk_fma_f32 v[160:161], v[28:29], v[14:15], v[160:161]
	v_pk_mul_f32 v[14:15], v[204:205], v[8:9] op_sel_hi:[1,0]
	v_pk_fma_f32 v[162:163], v[30:31], v[14:15], v[162:163]
	v_pk_mul_f32 v[14:15], v[206:207], v[8:9] op_sel_hi:[1,0]
	v_pk_fma_f32 v[164:165], v[32:33], v[14:15], v[164:165]
	v_pk_mul_f32 v[14:15], v[214:215], v[8:9] op_sel_hi:[1,0]
	v_pk_fma_f32 v[168:169], v[34:35], v[14:15], v[168:169]
	v_pk_mul_f32 v[14:15], v[216:217], v[8:9] op_sel_hi:[1,0]
	v_pk_fma_f32 v[170:171], v[36:37], v[14:15], v[170:171]
	v_pk_mul_f32 v[12:13], v[154:155], v[154:155]
	v_pk_fma_f32 v[12:13], v[156:157], v[156:157], v[12:13]
	v_pk_fma_f32 v[12:13], v[158:159], v[158:159], v[12:13]
	v_pk_fma_f32 v[12:13], v[160:161], v[160:161], v[12:13]
	v_pk_fma_f32 v[12:13], v[162:163], v[162:163], v[12:13]
	v_pk_fma_f32 v[12:13], v[164:165], v[164:165], v[12:13]
	v_pk_fma_f32 v[12:13], v[168:169], v[168:169], v[12:13]
	v_pk_fma_f32 v[12:13], v[170:171], v[170:171], v[12:13]
	v_add_f32_e32 v5, v12, v13
	s_nop 1
	v_add_f32_dpp v5, v5, v5 quad_perm:[1,0,3,2] row_mask:0xf bank_mask:0xf
	s_nop 1
	v_add_f32_dpp v5, v5, v5 quad_perm:[2,3,0,1] row_mask:0xf bank_mask:0xf
	s_nop 1
	v_add_f32_dpp v5, v5, v5 row_half_mirror row_mask:0xf bank_mask:0xf
	s_nop 1
	v_add_f32_dpp v5, v5, v5 row_mirror row_mask:0xf bank_mask:0xf
	s_nop 1
	v_add_f32_dpp v5, v5, v5 row_bcast:15 row_mask:0xa bank_mask:0xf
	s_nop 1
	v_add_f32_dpp v5, v5, v5 row_bcast:31 row_mask:0xc bank_mask:0xf
	s_nop 1
	v_readlane_b32 s32, v5, 63
	s_nop 1
	v_mov_b32_e32 v6, s32
	v_fmamk_f32 v6, v6, 0x3a800000, v146
	v_rsq_f32_e32 v6, v6
	s_nop 0
	v_mov_b32_e32 v10, v6
	v_pk_mul_f32 v[14:15], v[154:155], v[10:11] op_sel_hi:[1,0]
	v_pk_fma_f32 v[16:17], v[54:55], v[14:15], v[38:39]
	v_pk_mul_f32 v[14:15], v[156:157], v[10:11] op_sel_hi:[1,0]
	v_pk_fma_f32 v[18:19], v[56:57], v[14:15], v[40:41]
	v_cvt_pk_bf16_f32 v172, v16, v17
	v_cvt_pk_bf16_f32 v173, v18, v19
	v_pk_mul_f32 v[14:15], v[158:159], v[10:11] op_sel_hi:[1,0]
	v_pk_fma_f32 v[16:17], v[58:59], v[14:15], v[42:43]
	v_pk_mul_f32 v[14:15], v[160:161], v[10:11] op_sel_hi:[1,0]
	v_pk_fma_f32 v[18:19], v[60:61], v[14:15], v[44:45]
	v_cvt_pk_bf16_f32 v176, v16, v17
	v_cvt_pk_bf16_f32 v177, v18, v19
	v_pk_mul_f32 v[14:15], v[162:163], v[10:11] op_sel_hi:[1,0]
	v_pk_fma_f32 v[16:17], v[62:63], v[14:15], v[46:47]
	v_pk_mul_f32 v[14:15], v[164:165], v[10:11] op_sel_hi:[1,0]
	v_pk_fma_f32 v[18:19], v[64:65], v[14:15], v[48:49]
	v_cvt_pk_bf16_f32 v204, v16, v17
	v_cvt_pk_bf16_f32 v205, v18, v19
	v_pk_mul_f32 v[14:15], v[168:169], v[10:11] op_sel_hi:[1,0]
	v_pk_fma_f32 v[16:17], v[66:67], v[14:15], v[50:51]
	v_pk_mul_f32 v[14:15], v[170:171], v[10:11] op_sel_hi:[1,0]
	v_pk_fma_f32 v[18:19], v[68:69], v[14:15], v[52:53]
	v_cvt_pk_bf16_f32 v214, v16, v17
	v_cvt_pk_bf16_f32 v215, v18, v19
	global_store_dwordx2 v1, v[172:173], s[62:63] offset:0 sc1
	global_store_dwordx2 v1, v[176:177], s[62:63] offset:512 sc1
	global_store_dwordx2 v1, v[204:205], s[62:63] offset:1024 sc1
	global_store_dwordx2 v1, v[214:215], s[62:63] offset:1536 sc1
	global_store_dwordx4 v0, v[154:157], s[46:47] offset:0
	global_store_dwordx4 v0, v[158:161], s[46:47] offset:1024
	global_store_dwordx4 v0, v[162:165], s[46:47] offset:2048
	global_store_dwordx4 v0, v[168:171], s[46:47] offset:3072
	s_add_u32 s46, s46, 0x1000
	s_addc_u32 s47, s47, 0
	s_add_u32 s62, s62, 0x800
	s_addc_u32 s63, s63, 0
	s_waitcnt vmcnt(24)
	v_lshlrev_b32_e32 v14, 16, v234
	v_and_b32_e32 v15, 0xffff0000, v234
	v_lshlrev_b32_e32 v16, 16, v236
	v_and_b32_e32 v17, 0xffff0000, v236
	v_lshlrev_b32_e32 v18, 16, v235
	v_and_b32_e32 v19, 0xffff0000, v235
	v_lshlrev_b32_e32 v20, 16, v237
	v_and_b32_e32 v21, 0xffff0000, v237
	v_pk_add_f32 v[234:235], v[14:15], v[16:17]
	v_pk_add_f32 v[236:237], v[18:19], v[20:21]
	v_lshlrev_b32_e32 v14, 16, v238
	v_and_b32_e32 v15, 0xffff0000, v238
	v_lshlrev_b32_e32 v16, 16, v240
	v_and_b32_e32 v17, 0xffff0000, v240
	v_lshlrev_b32_e32 v18, 16, v239
	v_and_b32_e32 v19, 0xffff0000, v239
	v_lshlrev_b32_e32 v20, 16, v241
	v_and_b32_e32 v21, 0xffff0000, v241
	v_pk_add_f32 v[238:239], v[14:15], v[16:17]
	v_pk_add_f32 v[240:241], v[18:19], v[20:21]
	v_lshlrev_b32_e32 v14, 16, v242
	v_and_b32_e32 v15, 0xffff0000, v242
	v_lshlrev_b32_e32 v16, 16, v244
	v_and_b32_e32 v17, 0xffff0000, v244
	v_lshlrev_b32_e32 v18, 16, v243
	v_and_b32_e32 v19, 0xffff0000, v243
	v_lshlrev_b32_e32 v20, 16, v245
	v_and_b32_e32 v21, 0xffff0000, v245
	v_pk_add_f32 v[242:243], v[14:15], v[16:17]
	v_pk_add_f32 v[244:245], v[18:19], v[20:21]
	v_lshlrev_b32_e32 v14, 16, v246
	v_and_b32_e32 v15, 0xffff0000, v246
	v_lshlrev_b32_e32 v16, 16, v248
	v_and_b32_e32 v17, 0xffff0000, v248
	v_lshlrev_b32_e32 v18, 16, v247
	v_and_b32_e32 v19, 0xffff0000, v247
	v_lshlrev_b32_e32 v20, 16, v249
	v_and_b32_e32 v21, 0xffff0000, v249
	v_pk_add_f32 v[246:247], v[14:15], v[16:17]
	v_pk_add_f32 v[248:249], v[18:19], v[20:21]
	v_pk_mul_f32 v[12:13], v[234:235], v[234:235]
	v_pk_fma_f32 v[12:13], v[236:237], v[236:237], v[12:13]
	v_pk_fma_f32 v[12:13], v[238:239], v[238:239], v[12:13]
	v_pk_fma_f32 v[12:13], v[240:241], v[240:241], v[12:13]
	v_pk_fma_f32 v[12:13], v[242:243], v[242:243], v[12:13]
	v_pk_fma_f32 v[12:13], v[244:245], v[244:245], v[12:13]
	v_pk_fma_f32 v[12:13], v[246:247], v[246:247], v[12:13]
	v_pk_fma_f32 v[12:13], v[248:249], v[248:249], v[12:13]
	v_add_f32_e32 v5, v12, v13
	s_nop 1
	v_add_f32_dpp v5, v5, v5 quad_perm:[1,0,3,2] row_mask:0xf bank_mask:0xf
	s_nop 1
	v_add_f32_dpp v5, v5, v5 quad_perm:[2,3,0,1] row_mask:0xf bank_mask:0xf
	s_nop 1
	v_add_f32_dpp v5, v5, v5 row_half_mirror row_mask:0xf bank_mask:0xf
	s_nop 1
	v_add_f32_dpp v5, v5, v5 row_mirror row_mask:0xf bank_mask:0xf
	s_nop 1
	v_add_f32_dpp v5, v5, v5 row_bcast:15 row_mask:0xa bank_mask:0xf
	s_nop 1
	v_add_f32_dpp v5, v5, v5 row_bcast:31 row_mask:0xc bank_mask:0xf
	s_nop 1
	v_readlane_b32 s32, v5, 63
	s_nop 1
	v_mov_b32_e32 v6, s32
	v_fmamk_f32 v6, v6, 0x3a800000, v146
	v_rsq_f32_e32 v6, v6
	s_nop 0
	v_mul_f32_e32 v8, 0.5, v6
	v_pk_mul_f32 v[14:15], v[234:235], v[8:9] op_sel_hi:[1,0]
	v_pk_fma_f32 v[218:219], v[22:23], v[14:15], v[218:219]
	v_pk_mul_f32 v[14:15], v[236:237], v[8:9] op_sel_hi:[1,0]
	v_pk_fma_f32 v[220:221], v[24:25], v[14:15], v[220:221]
	v_pk_mul_f32 v[14:15], v[238:239], v[8:9] op_sel_hi:[1,0]
	v_pk_fma_f32 v[222:223], v[26:27], v[14:15], v[222:223]
	v_pk_mul_f32 v[14:15], v[240:241], v[8:9] op_sel_hi:[1,0]
	v_pk_fma_f32 v[224:225], v[28:29], v[14:15], v[224:225]
	v_pk_mul_f32 v[14:15], v[242:243], v[8:9] op_sel_hi:[1,0]
	v_pk_fma_f32 v[226:227], v[30:31], v[14:15], v[226:227]
	v_pk_mul_f32 v[14:15], v[244:245], v[8:9] op_sel_hi:[1,0]
	v_pk_fma_f32 v[228:229], v[32:33], v[14:15], v[228:229]
	v_pk_mul_f32 v[14:15], v[246:247], v[8:9] op_sel_hi:[1,0]
	v_pk_fma_f32 v[230:231], v[34:35], v[14:15], v[230:231]
	v_pk_mul_f32 v[14:15], v[248:249], v[8:9] op_sel_hi:[1,0]
	v_pk_fma_f32 v[232:233], v[36:37], v[14:15], v[232:233]
	v_pk_mul_f32 v[12:13], v[218:219], v[218:219]
	v_pk_fma_f32 v[12:13], v[220:221], v[220:221], v[12:13]
	v_pk_fma_f32 v[12:13], v[222:223], v[222:223], v[12:13]
	v_pk_fma_f32 v[12:13], v[224:225], v[224:225], v[12:13]
	v_pk_fma_f32 v[12:13], v[226:227], v[226:227], v[12:13]
	v_pk_fma_f32 v[12:13], v[228:229], v[228:229], v[12:13]
	v_pk_fma_f32 v[12:13], v[230:231], v[230:231], v[12:13]
	v_pk_fma_f32 v[12:13], v[232:233], v[232:233], v[12:13]
	v_add_f32_e32 v5, v12, v13
	s_nop 1
	v_add_f32_dpp v5, v5, v5 quad_perm:[1,0,3,2] row_mask:0xf bank_mask:0xf
	s_nop 1
	v_add_f32_dpp v5, v5, v5 quad_perm:[2,3,0,1] row_mask:0xf bank_mask:0xf
	s_nop 1
	v_add_f32_dpp v5, v5, v5 row_half_mirror row_mask:0xf bank_mask:0xf
	s_nop 1
	v_add_f32_dpp v5, v5, v5 row_mirror row_mask:0xf bank_mask:0xf
	s_nop 1
	v_add_f32_dpp v5, v5, v5 row_bcast:15 row_mask:0xa bank_mask:0xf
	s_nop 1
	v_add_f32_dpp v5, v5, v5 row_bcast:31 row_mask:0xc bank_mask:0xf
	s_nop 1
	v_readlane_b32 s32, v5, 63
	s_nop 1
	v_mov_b32_e32 v6, s32
	v_fmamk_f32 v6, v6, 0x3a800000, v146
	v_rsq_f32_e32 v6, v6
	s_nop 0
	v_mov_b32_e32 v10, v6
	v_pk_mul_f32 v[14:15], v[218:219], v[10:11] op_sel_hi:[1,0]
	v_pk_fma_f32 v[16:17], v[54:55], v[14:15], v[38:39]
	v_pk_mul_f32 v[14:15], v[220:221], v[10:11] op_sel_hi:[1,0]
	v_pk_fma_f32 v[18:19], v[56:57], v[14:15], v[40:41]
	v_cvt_pk_bf16_f32 v234, v16, v17
	v_cvt_pk_bf16_f32 v235, v18, v19
	v_pk_mul_f32 v[14:15], v[222:223], v[10:11] op_sel_hi:[1,0]
	v_pk_fma_f32 v[16:17], v[58:59], v[14:15], v[42:43]
	v_pk_mul_f32 v[14:15], v[224:225], v[10:11] op_sel_hi:[1,0]
	v_pk_fma_f32 v[18:19], v[60:61], v[14:15], v[44:45]
	v_cvt_pk_bf16_f32 v238, v16, v17
	v_cvt_pk_bf16_f32 v239, v18, v19
	v_pk_mul_f32 v[14:15], v[226:227], v[10:11] op_sel_hi:[1,0]
	v_pk_fma_f32 v[16:17], v[62:63], v[14:15], v[46:47]
	v_pk_mul_f32 v[14:15], v[228:229], v[10:11] op_sel_hi:[1,0]
	v_pk_fma_f32 v[18:19], v[64:65], v[14:15], v[48:49]
	v_cvt_pk_bf16_f32 v242, v16, v17
	v_cvt_pk_bf16_f32 v243, v18, v19
	v_pk_mul_f32 v[14:15], v[230:231], v[10:11] op_sel_hi:[1,0]
	v_pk_fma_f32 v[16:17], v[66:67], v[14:15], v[50:51]
	v_pk_mul_f32 v[14:15], v[232:233], v[10:11] op_sel_hi:[1,0]
	v_pk_fma_f32 v[18:19], v[68:69], v[14:15], v[52:53]
	v_cvt_pk_bf16_f32 v246, v16, v17
	v_cvt_pk_bf16_f32 v247, v18, v19
	global_store_dwordx2 v1, v[234:235], s[62:63] offset:0 sc1
	global_store_dwordx2 v1, v[238:239], s[62:63] offset:512 sc1
	global_store_dwordx2 v1, v[242:243], s[62:63] offset:1024 sc1
	global_store_dwordx2 v1, v[246:247], s[62:63] offset:1536 sc1
	global_store_dwordx4 v0, v[218:221], s[46:47] offset:0
	global_store_dwordx4 v0, v[222:225], s[46:47] offset:1024
	global_store_dwordx4 v0, v[226:229], s[46:47] offset:2048
	global_store_dwordx4 v0, v[230:233], s[46:47] offset:3072
	s_add_u32 s46, s46, 0x1000
	s_addc_u32 s47, s47, 0
	s_add_u32 s62, s62, 0x800
	s_addc_u32 s63, s63, 0

.Lnw_skip_n2:
	s_or_b64 exec, exec, s[40:41]
	s_barrier
	global_load_dwordx2 v[86:87], v1, s[58:59] offset:0
	global_load_dwordx2 v[90:91], v1, s[58:59] offset:512
	global_load_dwordx2 v[94:95], v1, s[58:59] offset:1024
	global_load_dwordx2 v[98:99], v1, s[58:59] offset:1536
	global_load_dwordx2 v[88:89], v1, s[60:61] offset:0
	global_load_dwordx2 v[92:93], v1, s[60:61] offset:512
	global_load_dwordx2 v[96:97], v1, s[60:61] offset:1024
	global_load_dwordx2 v[100:101], v1, s[60:61] offset:1536
	s_add_u32 s58, s58, 0x800
	s_addc_u32 s59, s59, 0
	s_add_u32 s60, s60, 0x800
	s_addc_u32 s61, s61, 0
	global_load_dwordx2 v[118:119], v1, s[58:59] offset:0
	global_load_dwordx2 v[122:123], v1, s[58:59] offset:512
	global_load_dwordx2 v[134:135], v1, s[58:59] offset:1024
	global_load_dwordx2 v[138:139], v1, s[58:59] offset:1536
	global_load_dwordx2 v[120:121], v1, s[60:61] offset:0
	global_load_dwordx2 v[124:125], v1, s[60:61] offset:512
	global_load_dwordx2 v[136:137], v1, s[60:61] offset:1024
	global_load_dwordx2 v[140:141], v1, s[60:61] offset:1536
	s_add_u32 s58, s58, 0x800
	s_addc_u32 s59, s59, 0
	s_add_u32 s60, s60, 0x800
	s_addc_u32 s61, s61, 0
	global_load_dwordx2 v[172:173], v1, s[58:59] offset:0
	global_load_dwordx2 v[176:177], v1, s[58:59] offset:512
	global_load_dwordx2 v[204:205], v1, s[58:59] offset:1024
	global_load_dwordx2 v[214:215], v1, s[58:59] offset:1536
	global_load_dwordx2 v[174:175], v1, s[60:61] offset:0
	global_load_dwordx2 v[178:179], v1, s[60:61] offset:512
	global_load_dwordx2 v[206:207], v1, s[60:61] offset:1024
	global_load_dwordx2 v[216:217], v1, s[60:61] offset:1536
	s_add_u32 s58, s58, 0x800
	s_addc_u32 s59, s59, 0
	s_add_u32 s60, s60, 0x800
	s_addc_u32 s61, s61, 0
	global_load_dwordx2 v[234:235], v1, s[58:59] offset:0
	global_load_dwordx2 v[238:239], v1, s[58:59] offset:512
	global_load_dwordx2 v[242:243], v1, s[58:59] offset:1024
	global_load_dwordx2 v[246:247], v1, s[58:59] offset:1536
	global_load_dwordx2 v[236:237], v1, s[60:61] offset:0
	global_load_dwordx2 v[240:241], v1, s[60:61] offset:512
	global_load_dwordx2 v[244:245], v1, s[60:61] offset:1024
	global_load_dwordx2 v[248:249], v1, s[60:61] offset:1536
	s_add_u32 s58, s58, 0x800
	s_addc_u32 s59, s59, 0
	s_add_u32 s60, s60, 0x800
	s_addc_u32 s61, s61, 0
	s_waitcnt vmcnt(24)
	v_lshlrev_b32_e32 v14, 16, v86
	v_and_b32_e32 v15, 0xffff0000, v86
	v_lshlrev_b32_e32 v16, 16, v88
	v_and_b32_e32 v17, 0xffff0000, v88
	v_lshlrev_b32_e32 v18, 16, v87
	v_and_b32_e32 v19, 0xffff0000, v87
	v_lshlrev_b32_e32 v20, 16, v89
	v_and_b32_e32 v21, 0xffff0000, v89
	v_pk_add_f32 v[86:87], v[14:15], v[16:17]
	v_pk_add_f32 v[88:89], v[18:19], v[20:21]
	v_lshlrev_b32_e32 v14, 16, v90
	v_and_b32_e32 v15, 0xffff0000, v90
	v_lshlrev_b32_e32 v16, 16, v92
	v_and_b32_e32 v17, 0xffff0000, v92
	v_lshlrev_b32_e32 v18, 16, v91
	v_and_b32_e32 v19, 0xffff0000, v91
	v_lshlrev_b32_e32 v20, 16, v93
	v_and_b32_e32 v21, 0xffff0000, v93
	v_pk_add_f32 v[90:91], v[14:15], v[16:17]
	v_pk_add_f32 v[92:93], v[18:19], v[20:21]
	v_lshlrev_b32_e32 v14, 16, v94
	v_and_b32_e32 v15, 0xffff0000, v94
	v_lshlrev_b32_e32 v16, 16, v96
	v_and_b32_e32 v17, 0xffff0000, v96
	v_lshlrev_b32_e32 v18, 16, v95
	v_and_b32_e32 v19, 0xffff0000, v95
	v_lshlrev_b32_e32 v20, 16, v97
	v_and_b32_e32 v21, 0xffff0000, v97
	v_pk_add_f32 v[94:95], v[14:15], v[16:17]
	v_pk_add_f32 v[96:97], v[18:19], v[20:21]
	v_lshlrev_b32_e32 v14, 16, v98
	v_and_b32_e32 v15, 0xffff0000, v98
	v_lshlrev_b32_e32 v16, 16, v100
	v_and_b32_e32 v17, 0xffff0000, v100
	v_lshlrev_b32_e32 v18, 16, v99
	v_and_b32_e32 v19, 0xffff0000, v99
	v_lshlrev_b32_e32 v20, 16, v101
	v_and_b32_e32 v21, 0xffff0000, v101
	v_pk_add_f32 v[98:99], v[14:15], v[16:17]
	v_pk_add_f32 v[100:101], v[18:19], v[20:21]
	v_pk_mul_f32 v[12:13], v[86:87], v[86:87]
	v_pk_fma_f32 v[12:13], v[88:89], v[88:89], v[12:13]
	v_pk_fma_f32 v[12:13], v[90:91], v[90:91], v[12:13]
	v_pk_fma_f32 v[12:13], v[92:93], v[92:93], v[12:13]
	v_pk_fma_f32 v[12:13], v[94:95], v[94:95], v[12:13]
	v_pk_fma_f32 v[12:13], v[96:97], v[96:97], v[12:13]
	v_pk_fma_f32 v[12:13], v[98:99], v[98:99], v[12:13]
	v_pk_fma_f32 v[12:13], v[100:101], v[100:101], v[12:13]
	v_add_f32_e32 v5, v12, v13
	s_nop 1
	v_add_f32_dpp v5, v5, v5 quad_perm:[1,0,3,2] row_mask:0xf bank_mask:0xf
	s_nop 1
	v_add_f32_dpp v5, v5, v5 quad_perm:[2,3,0,1] row_mask:0xf bank_mask:0xf
	s_nop 1
	v_add_f32_dpp v5, v5, v5 row_half_mirror row_mask:0xf bank_mask:0xf
	s_nop 1
	v_add_f32_dpp v5, v5, v5 row_mirror row_mask:0xf bank_mask:0xf
	s_nop 1
	v_add_f32_dpp v5, v5, v5 row_bcast:15 row_mask:0xa bank_mask:0xf
	s_nop 1
	v_add_f32_dpp v5, v5, v5 row_bcast:31 row_mask:0xc bank_mask:0xf
	s_nop 1
	v_readlane_b32 s32, v5, 63
	s_nop 1
	v_mov_b32_e32 v6, s32
	v_fmamk_f32 v6, v6, 0x3a800000, v146
	v_rsq_f32_e32 v6, v6
	s_nop 0
	v_mov_b32_e32 v8, v6
	v_pk_mul_f32 v[14:15], v[86:87], v[8:9] op_sel_hi:[1,0]
	v_pk_fma_f32 v[70:71], v[22:23], v[14:15], v[70:71]
	v_pk_mul_f32 v[14:15], v[88:89], v[8:9] op_sel_hi:[1,0]
	v_pk_fma_f32 v[72:73], v[24:25], v[14:15], v[72:73]
	v_pk_mul_f32 v[14:15], v[90:91], v[8:9] op_sel_hi:[1,0]
	v_pk_fma_f32 v[74:75], v[26:27], v[14:15], v[74:75]
	v_pk_mul_f32 v[14:15], v[92:93], v[8:9] op_sel_hi:[1,0]
	v_pk_fma_f32 v[76:77], v[28:29], v[14:15], v[76:77]
	v_pk_mul_f32 v[14:15], v[94:95], v[8:9] op_sel_hi:[1,0]
	v_pk_fma_f32 v[78:79], v[30:31], v[14:15], v[78:79]
	v_pk_mul_f32 v[14:15], v[96:97], v[8:9] op_sel_hi:[1,0]
	v_pk_fma_f32 v[80:81], v[32:33], v[14:15], v[80:81]
	v_pk_mul_f32 v[14:15], v[98:99], v[8:9] op_sel_hi:[1,0]
	v_pk_fma_f32 v[82:83], v[34:35], v[14:15], v[82:83]
	v_pk_mul_f32 v[14:15], v[100:101], v[8:9] op_sel_hi:[1,0]
	v_pk_fma_f32 v[84:85], v[36:37], v[14:15], v[84:85]
	v_pk_mul_f32 v[12:13], v[70:71], v[70:71]
	v_pk_fma_f32 v[12:13], v[72:73], v[72:73], v[12:13]
	v_pk_fma_f32 v[12:13], v[74:75], v[74:75], v[12:13]
	v_pk_fma_f32 v[12:13], v[76:77], v[76:77], v[12:13]
	v_pk_fma_f32 v[12:13], v[78:79], v[78:79], v[12:13]
	v_pk_fma_f32 v[12:13], v[80:81], v[80:81], v[12:13]
	v_pk_fma_f32 v[12:13], v[82:83], v[82:83], v[12:13]
	v_pk_fma_f32 v[12:13], v[84:85], v[84:85], v[12:13]
	v_add_f32_e32 v5, v12, v13
	s_nop 1
	v_add_f32_dpp v5, v5, v5 quad_perm:[1,0,3,2] row_mask:0xf bank_mask:0xf
	s_nop 1
	v_add_f32_dpp v5, v5, v5 quad_perm:[2,3,0,1] row_mask:0xf bank_mask:0xf
	s_nop 1
	v_add_f32_dpp v5, v5, v5 row_half_mirror row_mask:0xf bank_mask:0xf
	s_nop 1
	v_add_f32_dpp v5, v5, v5 row_mirror row_mask:0xf bank_mask:0xf
	s_nop 1
	v_add_f32_dpp v5, v5, v5 row_bcast:15 row_mask:0xa bank_mask:0xf
	s_nop 1
	v_add_f32_dpp v5, v5, v5 row_bcast:31 row_mask:0xc bank_mask:0xf
	s_nop 1
	v_readlane_b32 s32, v5, 63
	s_nop 1
	v_mov_b32_e32 v6, s32
	v_fmamk_f32 v6, v6, 0x3a800000, v146
	v_rsq_f32_e32 v6, v6
	s_nop 0
	v_mov_b32_e32 v10, v6
	v_pk_mul_f32 v[14:15], v[70:71], v[10:11] op_sel_hi:[1,0]
	v_pk_fma_f32 v[16:17], v[54:55], v[14:15], v[38:39]
	v_pk_mul_f32 v[14:15], v[72:73], v[10:11] op_sel_hi:[1,0]
	v_pk_fma_f32 v[18:19], v[56:57], v[14:15], v[40:41]
	v_cvt_pk_bf16_f32 v86, v16, v17
	v_cvt_pk_bf16_f32 v87, v18, v19
	v_pk_mul_f32 v[14:15], v[74:75], v[10:11] op_sel_hi:[1,0]
	v_pk_fma_f32 v[16:17], v[58:59], v[14:15], v[42:43]
	v_pk_mul_f32 v[14:15], v[76:77], v[10:11] op_sel_hi:[1,0]
	v_pk_fma_f32 v[18:19], v[60:61], v[14:15], v[44:45]
	v_cvt_pk_bf16_f32 v90, v16, v17
	v_cvt_pk_bf16_f32 v91, v18, v19
	v_pk_mul_f32 v[14:15], v[78:79], v[10:11] op_sel_hi:[1,0]
	v_pk_fma_f32 v[16:17], v[62:63], v[14:15], v[46:47]
	v_pk_mul_f32 v[14:15], v[80:81], v[10:11] op_sel_hi:[1,0]
	v_pk_fma_f32 v[18:19], v[64:65], v[14:15], v[48:49]
	v_cvt_pk_bf16_f32 v94, v16, v17
	v_cvt_pk_bf16_f32 v95, v18, v19
	v_pk_mul_f32 v[14:15], v[82:83], v[10:11] op_sel_hi:[1,0]
	v_pk_fma_f32 v[16:17], v[66:67], v[14:15], v[50:51]
	v_pk_mul_f32 v[14:15], v[84:85], v[10:11] op_sel_hi:[1,0]
	v_pk_fma_f32 v[18:19], v[68:69], v[14:15], v[52:53]
	v_cvt_pk_bf16_f32 v98, v16, v17
	v_cvt_pk_bf16_f32 v99, v18, v19
	global_store_dwordx2 v1, v[86:87], s[62:63] offset:0 sc1
	global_store_dwordx2 v1, v[90:91], s[62:63] offset:512 sc1
	global_store_dwordx2 v1, v[94:95], s[62:63] offset:1024 sc1
	global_store_dwordx2 v1, v[98:99], s[62:63] offset:1536 sc1
	global_store_dwordx4 v0, v[70:73], s[46:47] offset:0
	global_store_dwordx4 v0, v[74:77], s[46:47] offset:1024
	global_store_dwordx4 v0, v[78:81], s[46:47] offset:2048
	global_store_dwordx4 v0, v[82:85], s[46:47] offset:3072
	s_add_u32 s46, s46, 0x1000
	s_addc_u32 s47, s47, 0
	s_add_u32 s62, s62, 0x800
	s_addc_u32 s63, s63, 0
	s_waitcnt vmcnt(24)
	v_lshlrev_b32_e32 v14, 16, v118
	v_and_b32_e32 v15, 0xffff0000, v118
	v_lshlrev_b32_e32 v16, 16, v120
	v_and_b32_e32 v17, 0xffff0000, v120
	v_lshlrev_b32_e32 v18, 16, v119
	v_and_b32_e32 v19, 0xffff0000, v119
	v_lshlrev_b32_e32 v20, 16, v121
	v_and_b32_e32 v21, 0xffff0000, v121
	v_pk_add_f32 v[118:119], v[14:15], v[16:17]
	v_pk_add_f32 v[120:121], v[18:19], v[20:21]
	v_lshlrev_b32_e32 v14, 16, v122
	v_and_b32_e32 v15, 0xffff0000, v122
	v_lshlrev_b32_e32 v16, 16, v124
	v_and_b32_e32 v17, 0xffff0000, v124
	v_lshlrev_b32_e32 v18, 16, v123
	v_and_b32_e32 v19, 0xffff0000, v123
	v_lshlrev_b32_e32 v20, 16, v125
	v_and_b32_e32 v21, 0xffff0000, v125
	v_pk_add_f32 v[122:123], v[14:15], v[16:17]
	v_pk_add_f32 v[124:125], v[18:19], v[20:21]
	v_lshlrev_b32_e32 v14, 16, v134
	v_and_b32_e32 v15, 0xffff0000, v134
	v_lshlrev_b32_e32 v16, 16, v136
	v_and_b32_e32 v17, 0xffff0000, v136
	v_lshlrev_b32_e32 v18, 16, v135
	v_and_b32_e32 v19, 0xffff0000, v135
	v_lshlrev_b32_e32 v20, 16, v137
	v_and_b32_e32 v21, 0xffff0000, v137
	v_pk_add_f32 v[134:135], v[14:15], v[16:17]
	v_pk_add_f32 v[136:137], v[18:19], v[20:21]
	v_lshlrev_b32_e32 v14, 16, v138
	v_and_b32_e32 v15, 0xffff0000, v138
	v_lshlrev_b32_e32 v16, 16, v140
	v_and_b32_e32 v17, 0xffff0000, v140
	v_lshlrev_b32_e32 v18, 16, v139
	v_and_b32_e32 v19, 0xffff0000, v139
	v_lshlrev_b32_e32 v20, 16, v141
	v_and_b32_e32 v21, 0xffff0000, v141
	v_pk_add_f32 v[138:139], v[14:15], v[16:17]
	v_pk_add_f32 v[140:141], v[18:19], v[20:21]
	v_pk_mul_f32 v[12:13], v[118:119], v[118:119]
	v_pk_fma_f32 v[12:13], v[120:121], v[120:121], v[12:13]
	v_pk_fma_f32 v[12:13], v[122:123], v[122:123], v[12:13]
	v_pk_fma_f32 v[12:13], v[124:125], v[124:125], v[12:13]
	v_pk_fma_f32 v[12:13], v[134:135], v[134:135], v[12:13]
	v_pk_fma_f32 v[12:13], v[136:137], v[136:137], v[12:13]
	v_pk_fma_f32 v[12:13], v[138:139], v[138:139], v[12:13]
	v_pk_fma_f32 v[12:13], v[140:141], v[140:141], v[12:13]
	v_add_f32_e32 v5, v12, v13
	s_nop 1
	v_add_f32_dpp v5, v5, v5 quad_perm:[1,0,3,2] row_mask:0xf bank_mask:0xf
	s_nop 1
	v_add_f32_dpp v5, v5, v5 quad_perm:[2,3,0,1] row_mask:0xf bank_mask:0xf
	s_nop 1
	v_add_f32_dpp v5, v5, v5 row_half_mirror row_mask:0xf bank_mask:0xf
	s_nop 1
	v_add_f32_dpp v5, v5, v5 row_mirror row_mask:0xf bank_mask:0xf
	s_nop 1
	v_add_f32_dpp v5, v5, v5 row_bcast:15 row_mask:0xa bank_mask:0xf
	s_nop 1
	v_add_f32_dpp v5, v5, v5 row_bcast:31 row_mask:0xc bank_mask:0xf
	s_nop 1
	v_readlane_b32 s32, v5, 63
	s_nop 1
	v_mov_b32_e32 v6, s32
	v_fmamk_f32 v6, v6, 0x3a800000, v146
	v_rsq_f32_e32 v6, v6
	s_nop 0
	v_mov_b32_e32 v8, v6
	v_pk_mul_f32 v[14:15], v[118:119], v[8:9] op_sel_hi:[1,0]
	v_pk_fma_f32 v[102:103], v[22:23], v[14:15], v[102:103]
	v_pk_mul_f32 v[14:15], v[120:121], v[8:9] op_sel_hi:[1,0]
	v_pk_fma_f32 v[104:105], v[24:25], v[14:15], v[104:105]
	v_pk_mul_f32 v[14:15], v[122:123], v[8:9] op_sel_hi:[1,0]
	v_pk_fma_f32 v[106:107], v[26:27], v[14:15], v[106:107]
	v_pk_mul_f32 v[14:15], v[124:125], v[8:9] op_sel_hi:[1,0]
	v_pk_fma_f32 v[108:109], v[28:29], v[14:15], v[108:109]
	v_pk_mul_f32 v[14:15], v[134:135], v[8:9] op_sel_hi:[1,0]
	v_pk_fma_f32 v[110:111], v[30:31], v[14:15], v[110:111]
	v_pk_mul_f32 v[14:15], v[136:137], v[8:9] op_sel_hi:[1,0]
	v_pk_fma_f32 v[112:113], v[32:33], v[14:15], v[112:113]
	v_pk_mul_f32 v[14:15], v[138:139], v[8:9] op_sel_hi:[1,0]
	v_pk_fma_f32 v[114:115], v[34:35], v[14:15], v[114:115]
	v_pk_mul_f32 v[14:15], v[140:141], v[8:9] op_sel_hi:[1,0]
	v_pk_fma_f32 v[116:117], v[36:37], v[14:15], v[116:117]
	v_pk_mul_f32 v[12:13], v[102:103], v[102:103]
	v_pk_fma_f32 v[12:13], v[104:105], v[104:105], v[12:13]
	v_pk_fma_f32 v[12:13], v[106:107], v[106:107], v[12:13]
	v_pk_fma_f32 v[12:13], v[108:109], v[108:109], v[12:13]
	v_pk_fma_f32 v[12:13], v[110:111], v[110:111], v[12:13]
	v_pk_fma_f32 v[12:13], v[112:113], v[112:113], v[12:13]
	v_pk_fma_f32 v[12:13], v[114:115], v[114:115], v[12:13]
	v_pk_fma_f32 v[12:13], v[116:117], v[116:117], v[12:13]
	v_add_f32_e32 v5, v12, v13
	s_nop 1
	v_add_f32_dpp v5, v5, v5 quad_perm:[1,0,3,2] row_mask:0xf bank_mask:0xf
	s_nop 1
	v_add_f32_dpp v5, v5, v5 quad_perm:[2,3,0,1] row_mask:0xf bank_mask:0xf
	s_nop 1
	v_add_f32_dpp v5, v5, v5 row_half_mirror row_mask:0xf bank_mask:0xf
	s_nop 1
	v_add_f32_dpp v5, v5, v5 row_mirror row_mask:0xf bank_mask:0xf
	s_nop 1
	v_add_f32_dpp v5, v5, v5 row_bcast:15 row_mask:0xa bank_mask:0xf
	s_nop 1
	v_add_f32_dpp v5, v5, v5 row_bcast:31 row_mask:0xc bank_mask:0xf
	s_nop 1
	v_readlane_b32 s32, v5, 63
	s_nop 1
	v_mov_b32_e32 v6, s32
	v_fmamk_f32 v6, v6, 0x3a800000, v146
	v_rsq_f32_e32 v6, v6
	s_nop 0
	v_mov_b32_e32 v10, v6
	v_pk_mul_f32 v[14:15], v[102:103], v[10:11] op_sel_hi:[1,0]
	v_pk_fma_f32 v[16:17], v[54:55], v[14:15], v[38:39]
	v_pk_mul_f32 v[14:15], v[104:105], v[10:11] op_sel_hi:[1,0]
	v_pk_fma_f32 v[18:19], v[56:57], v[14:15], v[40:41]
	v_cvt_pk_bf16_f32 v118, v16, v17
	v_cvt_pk_bf16_f32 v119, v18, v19
	v_pk_mul_f32 v[14:15], v[106:107], v[10:11] op_sel_hi:[1,0]
	v_pk_fma_f32 v[16:17], v[58:59], v[14:15], v[42:43]
	v_pk_mul_f32 v[14:15], v[108:109], v[10:11] op_sel_hi:[1,0]
	v_pk_fma_f32 v[18:19], v[60:61], v[14:15], v[44:45]
	v_cvt_pk_bf16_f32 v122, v16, v17
	v_cvt_pk_bf16_f32 v123, v18, v19
	v_pk_mul_f32 v[14:15], v[110:111], v[10:11] op_sel_hi:[1,0]
	v_pk_fma_f32 v[16:17], v[62:63], v[14:15], v[46:47]
	v_pk_mul_f32 v[14:15], v[112:113], v[10:11] op_sel_hi:[1,0]
	v_pk_fma_f32 v[18:19], v[64:65], v[14:15], v[48:49]
	v_cvt_pk_bf16_f32 v134, v16, v17
	v_cvt_pk_bf16_f32 v135, v18, v19
	v_pk_mul_f32 v[14:15], v[114:115], v[10:11] op_sel_hi:[1,0]
	v_pk_fma_f32 v[16:17], v[66:67], v[14:15], v[50:51]
	v_pk_mul_f32 v[14:15], v[116:117], v[10:11] op_sel_hi:[1,0]
	v_pk_fma_f32 v[18:19], v[68:69], v[14:15], v[52:53]
	v_cvt_pk_bf16_f32 v138, v16, v17
	v_cvt_pk_bf16_f32 v139, v18, v19
	global_store_dwordx2 v1, v[118:119], s[62:63] offset:0 sc1
	global_store_dwordx2 v1, v[122:123], s[62:63] offset:512 sc1
	global_store_dwordx2 v1, v[134:135], s[62:63] offset:1024 sc1
	global_store_dwordx2 v1, v[138:139], s[62:63] offset:1536 sc1
	global_store_dwordx4 v0, v[102:105], s[46:47] offset:0
	global_store_dwordx4 v0, v[106:109], s[46:47] offset:1024
	global_store_dwordx4 v0, v[110:113], s[46:47] offset:2048
	global_store_dwordx4 v0, v[114:117], s[46:47] offset:3072
	s_add_u32 s46, s46, 0x1000
	s_addc_u32 s47, s47, 0
	s_add_u32 s62, s62, 0x800
	s_addc_u32 s63, s63, 0
	s_waitcnt vmcnt(24)
	v_lshlrev_b32_e32 v14, 16, v172
	v_and_b32_e32 v15, 0xffff0000, v172
	v_lshlrev_b32_e32 v16, 16, v174
	v_and_b32_e32 v17, 0xffff0000, v174
	v_lshlrev_b32_e32 v18, 16, v173
	v_and_b32_e32 v19, 0xffff0000, v173
	v_lshlrev_b32_e32 v20, 16, v175
	v_and_b32_e32 v21, 0xffff0000, v175
	v_pk_add_f32 v[172:173], v[14:15], v[16:17]
	v_pk_add_f32 v[174:175], v[18:19], v[20:21]
	v_lshlrev_b32_e32 v14, 16, v176
	v_and_b32_e32 v15, 0xffff0000, v176
	v_lshlrev_b32_e32 v16, 16, v178
	v_and_b32_e32 v17, 0xffff0000, v178
	v_lshlrev_b32_e32 v18, 16, v177
	v_and_b32_e32 v19, 0xffff0000, v177
	v_lshlrev_b32_e32 v20, 16, v179
	v_and_b32_e32 v21, 0xffff0000, v179
	v_pk_add_f32 v[176:177], v[14:15], v[16:17]
	v_pk_add_f32 v[178:179], v[18:19], v[20:21]
	v_lshlrev_b32_e32 v14, 16, v204
	v_and_b32_e32 v15, 0xffff0000, v204
	v_lshlrev_b32_e32 v16, 16, v206
	v_and_b32_e32 v17, 0xffff0000, v206
	v_lshlrev_b32_e32 v18, 16, v205
	v_and_b32_e32 v19, 0xffff0000, v205
	v_lshlrev_b32_e32 v20, 16, v207
	v_and_b32_e32 v21, 0xffff0000, v207
	v_pk_add_f32 v[204:205], v[14:15], v[16:17]
	v_pk_add_f32 v[206:207], v[18:19], v[20:21]
	v_lshlrev_b32_e32 v14, 16, v214
	v_and_b32_e32 v15, 0xffff0000, v214
	v_lshlrev_b32_e32 v16, 16, v216
	v_and_b32_e32 v17, 0xffff0000, v216
	v_lshlrev_b32_e32 v18, 16, v215
	v_and_b32_e32 v19, 0xffff0000, v215
	v_lshlrev_b32_e32 v20, 16, v217
	v_and_b32_e32 v21, 0xffff0000, v217
	v_pk_add_f32 v[214:215], v[14:15], v[16:17]
	v_pk_add_f32 v[216:217], v[18:19], v[20:21]
	v_pk_mul_f32 v[12:13], v[172:173], v[172:173]
	v_pk_fma_f32 v[12:13], v[174:175], v[174:175], v[12:13]
	v_pk_fma_f32 v[12:13], v[176:177], v[176:177], v[12:13]
	v_pk_fma_f32 v[12:13], v[178:179], v[178:179], v[12:13]
	v_pk_fma_f32 v[12:13], v[204:205], v[204:205], v[12:13]
	v_pk_fma_f32 v[12:13], v[206:207], v[206:207], v[12:13]
	v_pk_fma_f32 v[12:13], v[214:215], v[214:215], v[12:13]
	v_pk_fma_f32 v[12:13], v[216:217], v[216:217], v[12:13]
	v_add_f32_e32 v5, v12, v13
	s_nop 1
	v_add_f32_dpp v5, v5, v5 quad_perm:[1,0,3,2] row_mask:0xf bank_mask:0xf
	s_nop 1
	v_add_f32_dpp v5, v5, v5 quad_perm:[2,3,0,1] row_mask:0xf bank_mask:0xf
	s_nop 1
	v_add_f32_dpp v5, v5, v5 row_half_mirror row_mask:0xf bank_mask:0xf
	s_nop 1
	v_add_f32_dpp v5, v5, v5 row_mirror row_mask:0xf bank_mask:0xf
	s_nop 1
	v_add_f32_dpp v5, v5, v5 row_bcast:15 row_mask:0xa bank_mask:0xf
	s_nop 1
	v_add_f32_dpp v5, v5, v5 row_bcast:31 row_mask:0xc bank_mask:0xf
	s_nop 1
	v_readlane_b32 s32, v5, 63
	s_nop 1
	v_mov_b32_e32 v6, s32
	v_fmamk_f32 v6, v6, 0x3a800000, v146
	v_rsq_f32_e32 v6, v6
	s_nop 0
	v_mov_b32_e32 v8, v6
	v_pk_mul_f32 v[14:15], v[172:173], v[8:9] op_sel_hi:[1,0]
	v_pk_fma_f32 v[154:155], v[22:23], v[14:15], v[154:155]
	v_pk_mul_f32 v[14:15], v[174:175], v[8:9] op_sel_hi:[1,0]
	v_pk_fma_f32 v[156:157], v[24:25], v[14:15], v[156:157]
	v_pk_mul_f32 v[14:15], v[176:177], v[8:9] op_sel_hi:[1,0]
	v_pk_fma_f32 v[158:159], v[26:27], v[14:15], v[158:159]
	v_pk_mul_f32 v[14:15], v[178:179], v[8:9] op_sel_hi:[1,0]
	v_pk_fma_f32 v[160:161], v[28:29], v[14:15], v[160:161]
	v_pk_mul_f32 v[14:15], v[204:205], v[8:9] op_sel_hi:[1,0]
	v_pk_fma_f32 v[162:163], v[30:31], v[14:15], v[162:163]
	v_pk_mul_f32 v[14:15], v[206:207], v[8:9] op_sel_hi:[1,0]
	v_pk_fma_f32 v[164:165], v[32:33], v[14:15], v[164:165]
	v_pk_mul_f32 v[14:15], v[214:215], v[8:9] op_sel_hi:[1,0]
	v_pk_fma_f32 v[168:169], v[34:35], v[14:15], v[168:169]
	v_pk_mul_f32 v[14:15], v[216:217], v[8:9] op_sel_hi:[1,0]
	v_pk_fma_f32 v[170:171], v[36:37], v[14:15], v[170:171]
	v_pk_mul_f32 v[12:13], v[154:155], v[154:155]
	v_pk_fma_f32 v[12:13], v[156:157], v[156:157], v[12:13]
	v_pk_fma_f32 v[12:13], v[158:159], v[158:159], v[12:13]
	v_pk_fma_f32 v[12:13], v[160:161], v[160:161], v[12:13]
	v_pk_fma_f32 v[12:13], v[162:163], v[162:163], v[12:13]
	v_pk_fma_f32 v[12:13], v[164:165], v[164:165], v[12:13]
	v_pk_fma_f32 v[12:13], v[168:169], v[168:169], v[12:13]
	v_pk_fma_f32 v[12:13], v[170:171], v[170:171], v[12:13]
	v_add_f32_e32 v5, v12, v13
	s_nop 1
	v_add_f32_dpp v5, v5, v5 quad_perm:[1,0,3,2] row_mask:0xf bank_mask:0xf
	s_nop 1
	v_add_f32_dpp v5, v5, v5 quad_perm:[2,3,0,1] row_mask:0xf bank_mask:0xf
	s_nop 1
	v_add_f32_dpp v5, v5, v5 row_half_mirror row_mask:0xf bank_mask:0xf
	s_nop 1
	v_add_f32_dpp v5, v5, v5 row_mirror row_mask:0xf bank_mask:0xf
	s_nop 1
	v_add_f32_dpp v5, v5, v5 row_bcast:15 row_mask:0xa bank_mask:0xf
	s_nop 1
	v_add_f32_dpp v5, v5, v5 row_bcast:31 row_mask:0xc bank_mask:0xf
	s_nop 1
	v_readlane_b32 s32, v5, 63
	s_nop 1
	v_mov_b32_e32 v6, s32
	v_fmamk_f32 v6, v6, 0x3a800000, v146
	v_rsq_f32_e32 v6, v6
	s_nop 0
	v_mov_b32_e32 v10, v6
	v_pk_mul_f32 v[14:15], v[154:155], v[10:11] op_sel_hi:[1,0]
	v_pk_fma_f32 v[16:17], v[54:55], v[14:15], v[38:39]
	v_pk_mul_f32 v[14:15], v[156:157], v[10:11] op_sel_hi:[1,0]
	v_pk_fma_f32 v[18:19], v[56:57], v[14:15], v[40:41]
	v_cvt_pk_bf16_f32 v172, v16, v17
	v_cvt_pk_bf16_f32 v173, v18, v19
	v_pk_mul_f32 v[14:15], v[158:159], v[10:11] op_sel_hi:[1,0]
	v_pk_fma_f32 v[16:17], v[58:59], v[14:15], v[42:43]
	v_pk_mul_f32 v[14:15], v[160:161], v[10:11] op_sel_hi:[1,0]
	v_pk_fma_f32 v[18:19], v[60:61], v[14:15], v[44:45]
	v_cvt_pk_bf16_f32 v176, v16, v17
	v_cvt_pk_bf16_f32 v177, v18, v19
	v_pk_mul_f32 v[14:15], v[162:163], v[10:11] op_sel_hi:[1,0]
	v_pk_fma_f32 v[16:17], v[62:63], v[14:15], v[46:47]
	v_pk_mul_f32 v[14:15], v[164:165], v[10:11] op_sel_hi:[1,0]
	v_pk_fma_f32 v[18:19], v[64:65], v[14:15], v[48:49]
	v_cvt_pk_bf16_f32 v204, v16, v17
	v_cvt_pk_bf16_f32 v205, v18, v19
	v_pk_mul_f32 v[14:15], v[168:169], v[10:11] op_sel_hi:[1,0]
	v_pk_fma_f32 v[16:17], v[66:67], v[14:15], v[50:51]
	v_pk_mul_f32 v[14:15], v[170:171], v[10:11] op_sel_hi:[1,0]
	v_pk_fma_f32 v[18:19], v[68:69], v[14:15], v[52:53]
	v_cvt_pk_bf16_f32 v214, v16, v17
	v_cvt_pk_bf16_f32 v215, v18, v19
	global_store_dwordx2 v1, v[172:173], s[62:63] offset:0 sc1
	global_store_dwordx2 v1, v[176:177], s[62:63] offset:512 sc1
	global_store_dwordx2 v1, v[204:205], s[62:63] offset:1024 sc1
	global_store_dwordx2 v1, v[214:215], s[62:63] offset:1536 sc1
	global_store_dwordx4 v0, v[154:157], s[46:47] offset:0
	global_store_dwordx4 v0, v[158:161], s[46:47] offset:1024
	global_store_dwordx4 v0, v[162:165], s[46:47] offset:2048
	global_store_dwordx4 v0, v[168:171], s[46:47] offset:3072
	s_add_u32 s46, s46, 0x1000
	s_addc_u32 s47, s47, 0
	s_add_u32 s62, s62, 0x800
	s_addc_u32 s63, s63, 0
	s_waitcnt vmcnt(24)
	v_lshlrev_b32_e32 v14, 16, v234
	v_and_b32_e32 v15, 0xffff0000, v234
	v_lshlrev_b32_e32 v16, 16, v236
	v_and_b32_e32 v17, 0xffff0000, v236
	v_lshlrev_b32_e32 v18, 16, v235
	v_and_b32_e32 v19, 0xffff0000, v235
	v_lshlrev_b32_e32 v20, 16, v237
	v_and_b32_e32 v21, 0xffff0000, v237
	v_pk_add_f32 v[234:235], v[14:15], v[16:17]
	v_pk_add_f32 v[236:237], v[18:19], v[20:21]
	v_lshlrev_b32_e32 v14, 16, v238
	v_and_b32_e32 v15, 0xffff0000, v238
	v_lshlrev_b32_e32 v16, 16, v240
	v_and_b32_e32 v17, 0xffff0000, v240
	v_lshlrev_b32_e32 v18, 16, v239
	v_and_b32_e32 v19, 0xffff0000, v239
	v_lshlrev_b32_e32 v20, 16, v241
	v_and_b32_e32 v21, 0xffff0000, v241
	v_pk_add_f32 v[238:239], v[14:15], v[16:17]
	v_pk_add_f32 v[240:241], v[18:19], v[20:21]
	v_lshlrev_b32_e32 v14, 16, v242
	v_and_b32_e32 v15, 0xffff0000, v242
	v_lshlrev_b32_e32 v16, 16, v244
	v_and_b32_e32 v17, 0xffff0000, v244
	v_lshlrev_b32_e32 v18, 16, v243
	v_and_b32_e32 v19, 0xffff0000, v243
	v_lshlrev_b32_e32 v20, 16, v245
	v_and_b32_e32 v21, 0xffff0000, v245
	v_pk_add_f32 v[242:243], v[14:15], v[16:17]
	v_pk_add_f32 v[244:245], v[18:19], v[20:21]
	v_lshlrev_b32_e32 v14, 16, v246
	v_and_b32_e32 v15, 0xffff0000, v246
	v_lshlrev_b32_e32 v16, 16, v248
	v_and_b32_e32 v17, 0xffff0000, v248
	v_lshlrev_b32_e32 v18, 16, v247
	v_and_b32_e32 v19, 0xffff0000, v247
	v_lshlrev_b32_e32 v20, 16, v249
	v_and_b32_e32 v21, 0xffff0000, v249
	v_pk_add_f32 v[246:247], v[14:15], v[16:17]
	v_pk_add_f32 v[248:249], v[18:19], v[20:21]
	v_pk_mul_f32 v[12:13], v[234:235], v[234:235]
	v_pk_fma_f32 v[12:13], v[236:237], v[236:237], v[12:13]
	v_pk_fma_f32 v[12:13], v[238:239], v[238:239], v[12:13]
	v_pk_fma_f32 v[12:13], v[240:241], v[240:241], v[12:13]
	v_pk_fma_f32 v[12:13], v[242:243], v[242:243], v[12:13]
	v_pk_fma_f32 v[12:13], v[244:245], v[244:245], v[12:13]
	v_pk_fma_f32 v[12:13], v[246:247], v[246:247], v[12:13]
	v_pk_fma_f32 v[12:13], v[248:249], v[248:249], v[12:13]
	v_add_f32_e32 v5, v12, v13
	s_nop 1
	v_add_f32_dpp v5, v5, v5 quad_perm:[1,0,3,2] row_mask:0xf bank_mask:0xf
	s_nop 1
	v_add_f32_dpp v5, v5, v5 quad_perm:[2,3,0,1] row_mask:0xf bank_mask:0xf
	s_nop 1
	v_add_f32_dpp v5, v5, v5 row_half_mirror row_mask:0xf bank_mask:0xf
	s_nop 1
	v_add_f32_dpp v5, v5, v5 row_mirror row_mask:0xf bank_mask:0xf
	s_nop 1
	v_add_f32_dpp v5, v5, v5 row_bcast:15 row_mask:0xa bank_mask:0xf
	s_nop 1
	v_add_f32_dpp v5, v5, v5 row_bcast:31 row_mask:0xc bank_mask:0xf
	s_nop 1
	v_readlane_b32 s32, v5, 63
	s_nop 1
	v_mov_b32_e32 v6, s32
	v_fmamk_f32 v6, v6, 0x3a800000, v146
	v_rsq_f32_e32 v6, v6
	s_nop 0
	v_mov_b32_e32 v8, v6
	v_pk_mul_f32 v[14:15], v[234:235], v[8:9] op_sel_hi:[1,0]
	v_pk_fma_f32 v[218:219], v[22:23], v[14:15], v[218:219]
	v_pk_mul_f32 v[14:15], v[236:237], v[8:9] op_sel_hi:[1,0]
	v_pk_fma_f32 v[220:221], v[24:25], v[14:15], v[220:221]
	v_pk_mul_f32 v[14:15], v[238:239], v[8:9] op_sel_hi:[1,0]
	v_pk_fma_f32 v[222:223], v[26:27], v[14:15], v[222:223]
	v_pk_mul_f32 v[14:15], v[240:241], v[8:9] op_sel_hi:[1,0]
	v_pk_fma_f32 v[224:225], v[28:29], v[14:15], v[224:225]
	v_pk_mul_f32 v[14:15], v[242:243], v[8:9] op_sel_hi:[1,0]
	v_pk_fma_f32 v[226:227], v[30:31], v[14:15], v[226:227]
	v_pk_mul_f32 v[14:15], v[244:245], v[8:9] op_sel_hi:[1,0]
	v_pk_fma_f32 v[228:229], v[32:33], v[14:15], v[228:229]
	v_pk_mul_f32 v[14:15], v[246:247], v[8:9] op_sel_hi:[1,0]
	v_pk_fma_f32 v[230:231], v[34:35], v[14:15], v[230:231]
	v_pk_mul_f32 v[14:15], v[248:249], v[8:9] op_sel_hi:[1,0]
	v_pk_fma_f32 v[232:233], v[36:37], v[14:15], v[232:233]
	v_pk_mul_f32 v[12:13], v[218:219], v[218:219]
	v_pk_fma_f32 v[12:13], v[220:221], v[220:221], v[12:13]
	v_pk_fma_f32 v[12:13], v[222:223], v[222:223], v[12:13]
	v_pk_fma_f32 v[12:13], v[224:225], v[224:225], v[12:13]
	v_pk_fma_f32 v[12:13], v[226:227], v[226:227], v[12:13]
	v_pk_fma_f32 v[12:13], v[228:229], v[228:229], v[12:13]
	v_pk_fma_f32 v[12:13], v[230:231], v[230:231], v[12:13]
	v_pk_fma_f32 v[12:13], v[232:233], v[232:233], v[12:13]
	v_add_f32_e32 v5, v12, v13
	s_nop 1
	v_add_f32_dpp v5, v5, v5 quad_perm:[1,0,3,2] row_mask:0xf bank_mask:0xf
	s_nop 1
	v_add_f32_dpp v5, v5, v5 quad_perm:[2,3,0,1] row_mask:0xf bank_mask:0xf
	s_nop 1
	v_add_f32_dpp v5, v5, v5 row_half_mirror row_mask:0xf bank_mask:0xf
	s_nop 1
	v_add_f32_dpp v5, v5, v5 row_mirror row_mask:0xf bank_mask:0xf
	s_nop 1
	v_add_f32_dpp v5, v5, v5 row_bcast:15 row_mask:0xa bank_mask:0xf
	s_nop 1
	v_add_f32_dpp v5, v5, v5 row_bcast:31 row_mask:0xc bank_mask:0xf
	s_nop 1
	v_readlane_b32 s32, v5, 63
	s_nop 1
	v_mov_b32_e32 v6, s32
	v_fmamk_f32 v6, v6, 0x3a800000, v146
	v_rsq_f32_e32 v6, v6
	s_nop 0
	v_mov_b32_e32 v10, v6
	v_pk_mul_f32 v[14:15], v[218:219], v[10:11] op_sel_hi:[1,0]
	v_pk_fma_f32 v[16:17], v[54:55], v[14:15], v[38:39]
	v_pk_mul_f32 v[14:15], v[220:221], v[10:11] op_sel_hi:[1,0]
	v_pk_fma_f32 v[18:19], v[56:57], v[14:15], v[40:41]
	v_cvt_pk_bf16_f32 v234, v16, v17
	v_cvt_pk_bf16_f32 v235, v18, v19
	v_pk_mul_f32 v[14:15], v[222:223], v[10:11] op_sel_hi:[1,0]
	v_pk_fma_f32 v[16:17], v[58:59], v[14:15], v[42:43]
	v_pk_mul_f32 v[14:15], v[224:225], v[10:11] op_sel_hi:[1,0]
	v_pk_fma_f32 v[18:19], v[60:61], v[14:15], v[44:45]
	v_cvt_pk_bf16_f32 v238, v16, v17
	v_cvt_pk_bf16_f32 v239, v18, v19
	v_pk_mul_f32 v[14:15], v[226:227], v[10:11] op_sel_hi:[1,0]
	v_pk_fma_f32 v[16:17], v[62:63], v[14:15], v[46:47]
	v_pk_mul_f32 v[14:15], v[228:229], v[10:11] op_sel_hi:[1,0]
	v_pk_fma_f32 v[18:19], v[64:65], v[14:15], v[48:49]
	v_cvt_pk_bf16_f32 v242, v16, v17
	v_cvt_pk_bf16_f32 v243, v18, v19
	v_pk_mul_f32 v[14:15], v[230:231], v[10:11] op_sel_hi:[1,0]
	v_pk_fma_f32 v[16:17], v[66:67], v[14:15], v[50:51]
	v_pk_mul_f32 v[14:15], v[232:233], v[10:11] op_sel_hi:[1,0]
	v_pk_fma_f32 v[18:19], v[68:69], v[14:15], v[52:53]
	v_cvt_pk_bf16_f32 v246, v16, v17
	v_cvt_pk_bf16_f32 v247, v18, v19
	global_store_dwordx2 v1, v[234:235], s[62:63] offset:0 sc1
	global_store_dwordx2 v1, v[238:239], s[62:63] offset:512 sc1
	global_store_dwordx2 v1, v[242:243], s[62:63] offset:1024 sc1
	global_store_dwordx2 v1, v[246:247], s[62:63] offset:1536 sc1
	global_store_dwordx4 v0, v[218:221], s[46:47] offset:0
	global_store_dwordx4 v0, v[222:225], s[46:47] offset:1024
	global_store_dwordx4 v0, v[226:229], s[46:47] offset:2048
	global_store_dwordx4 v0, v[230:233], s[46:47] offset:3072
	s_add_u32 s46, s46, 0x1000
	s_addc_u32 s47, s47, 0
	s_add_u32 s62, s62, 0x800
	s_addc_u32 s63, s63, 0
